# P0 row loop rewritten by hand: packed f32 FMAs for forget-gate dots, DPP reductions, log-sigmoid batched per 8 rows on 64 lanes, 3-row prefetch
# baseline (speedup 1.0000x reference)
; #define GAS __attribute__((address_space(1)))
; __device__ __forceinline__ void p0_prologue(const Args& a, LAS unsigned char* lds, int vcu, int G, int tid, int lane, int wave) {
;     ...
;     const GAS f32x4* gp = (const GAS f32x4*)n1g + lane;
;     f32x4 gv[4];
; #pragma unroll
;     for (int j = 0; j < 4; ++j) gv[j] = gp[64 * j];
;     f32x4 nv[4];
;     if (gw < T) { const GAS f32x4* xr0 = (const GAS f32x4*)(x + (size_t)gw * DM) + lane;
; #pragma unroll
;         for (int j = 0; j < 4; ++j) nv[j] = xr0[64 * j]; }
;     for (int m = gw; m < T; m += NGW) {
;         f32x4 v[4]; float s2 = 0.f;
; #pragma unroll
;         for (int j = 0; j < 4; ++j) { v[j] = nv[j]; s2 += (v[j].x * v[j].x + v[j].y * v[j].y) + (v[j].z * v[j].z + v[j].w * v[j].w); }
;         if (m + NGW < T) { const GAS f32x4* xr = (const GAS f32x4*)(x + (size_t)(m + NGW) * DM) + lane;
; #pragma unroll
;             for (int j = 0; j < 4; ++j) nv[j] = xr[64 * j]; }
;         const float rstd = 1.0f / sqrtf(wave_sum(s2) * (1.f / DM) + EPS);
; #pragma unroll
;         for (int j = 0; j < 4; ++j) v[j] = v[j] * rstd * gv[j];
.Lp0r_entry:
	v_and_b32_e32 v1, 63, v0
	v_lshlrev_b32_e32 v2, 4, v1
	v_lshlrev_b32_e32 v3, 3, v1
	global_load_dwordx4 v[112:115], v2, s[38:39] offset:0
	global_load_dwordx4 v[116:119], v2, s[38:39] offset:1024
	global_load_dwordx4 v[120:123], v2, s[38:39] offset:2048
	global_load_dwordx4 v[124:127], v2, s[38:39] offset:3072
	v_and_b32_e32 v38, 7, v1
	v_lshlrev_b32_e32 v38, 2, v38
	global_load_dword v5, v38, s[50:51]
	s_lshl_b32 s0, s62, 12
	s_add_u32 s0, s36, s0
	s_addc_u32 s1, s37, 0
	global_load_dwordx4 v[48:51], v2, s[0:1] offset:0
	global_load_dwordx4 v[52:55], v2, s[0:1] offset:1024
	global_load_dwordx4 v[56:59], v2, s[0:1] offset:2048
	global_load_dwordx4 v[60:63], v2, s[0:1] offset:3072
	s_add_i32 s8, s62, s34
	s_cmp_lt_i32 s8, 32768
	s_cbranch_scc0 .Lp0r_pro
	s_lshl_b32 s0, s8, 12
	s_add_u32 s0, s36, s0
	s_addc_u32 s1, s37, 0
	global_load_dwordx4 v[64:67], v2, s[0:1] offset:0
	global_load_dwordx4 v[68:71], v2, s[0:1] offset:1024
	global_load_dwordx4 v[72:75], v2, s[0:1] offset:2048
	global_load_dwordx4 v[76:79], v2, s[0:1] offset:3072
	s_add_i32 s8, s8, s34
	s_cmp_lt_i32 s8, 32768
	s_cbranch_scc0 .Lp0r_pro
	s_lshl_b32 s0, s8, 12
	s_add_u32 s0, s36, s0
	s_addc_u32 s1, s37, 0
	global_load_dwordx4 v[80:83], v2, s[0:1] offset:0
	global_load_dwordx4 v[84:87], v2, s[0:1] offset:1024
	global_load_dwordx4 v[88:91], v2, s[0:1] offset:2048
	global_load_dwordx4 v[92:95], v2, s[0:1] offset:3072
.Lp0r_pro:
	v_add_u32_e32 v39, 0x12000, v2
	ds_read_b128 v[128:131], v39 offset:0
	ds_read_b128 v[132:135], v39 offset:1024
	ds_read_b128 v[136:139], v39 offset:2048
	ds_read_b128 v[140:143], v39 offset:3072
	ds_read_b128 v[144:147], v39 offset:4096
	ds_read_b128 v[148:151], v39 offset:5120
	ds_read_b128 v[152:155], v39 offset:6144
	ds_read_b128 v[156:159], v39 offset:7168
	s_waitcnt lgkmcnt(0)
	ds_read_b128 v[160:163], v39 offset:8192
	ds_read_b128 v[164:167], v39 offset:9216
	ds_read_b128 v[168:171], v39 offset:10240
	ds_read_b128 v[172:175], v39 offset:11264
	ds_read_b128 v[176:179], v39 offset:12288
	ds_read_b128 v[180:183], v39 offset:13312
	ds_read_b128 v[184:187], v39 offset:14336
	ds_read_b128 v[188:191], v39 offset:15360
	s_waitcnt lgkmcnt(0)
	ds_read_b128 v[192:195], v39 offset:16384
	ds_read_b128 v[196:199], v39 offset:17408
	ds_read_b128 v[200:203], v39 offset:18432
	ds_read_b128 v[204:207], v39 offset:19456
	ds_read_b128 v[208:211], v39 offset:20480
	ds_read_b128 v[212:215], v39 offset:21504
	ds_read_b128 v[216:219], v39 offset:22528
	ds_read_b128 v[220:223], v39 offset:23552
	s_waitcnt lgkmcnt(0)
	ds_read_b128 v[224:227], v39 offset:24576
	ds_read_b128 v[228:231], v39 offset:25600
	ds_read_b128 v[232:235], v39 offset:26624
	ds_read_b128 v[236:239], v39 offset:27648
	ds_read_b128 v[240:243], v39 offset:28672
	ds_read_b128 v[244:247], v39 offset:29696
	ds_read_b128 v[248:251], v39 offset:30720
	ds_read_b128 v[252:255], v39 offset:31744
	s_waitcnt lgkmcnt(0)
	s_mov_b32 s35, 0xbfb8aa3b
	s_mov_b32 s54, 0xb2a5705f
	s_mov_b32 s55, 0x42ce8ed0
	s_mov_b32 s56, 0xc2b17218
	s_mov_b32 s57, 0x7f800000
	s_mov_b32 s58, 0x3f2aaaab
	s_mov_b32 s59, 0x3f317218
	s_mov_b32 s63, 0x33800000
	v_mov_b32_e32 v32, 0x3f317218
	v_mov_b32_e32 v36, 0x3ecc95a3
	v_mov_b32_e32 v37, 0x7f800000
	v_mov_b32_e32 v4, 0
	s_mov_b32 s64, s62
	s_mov_b32 s5, 0
	s_waitcnt vmcnt(0) lgkmcnt(0)
.Lp0r_row0:
	s_add_i32 s8, s62, s34
	s_add_i32 s10, s8, s34
	s_add_i32 s11, s10, s34
	s_cmp_lt_i32 s10, 32768
	s_cbranch_scc1 .Lp0r_w20_0
	s_cmp_lt_i32 s8, 32768
	s_cbranch_scc1 .Lp0r_w16_0
	s_waitcnt vmcnt(12)
	s_branch .Lp0r_wd_0
.Lp0r_w16_0:
	s_waitcnt vmcnt(16)
	s_branch .Lp0r_wd_0
.Lp0r_w20_0:
	s_waitcnt vmcnt(20)
.Lp0r_wd_0:
	s_cmp_lt_i32 s11, 32768
	s_cbranch_scc0 .Lp0r_nl_0
	s_lshl_b32 s0, s11, 12
	s_add_u32 s0, s36, s0
	s_addc_u32 s1, s37, 0
	global_load_dwordx4 v[96:99], v2, s[0:1] offset:0
	global_load_dwordx4 v[100:103], v2, s[0:1] offset:1024
	global_load_dwordx4 v[104:107], v2, s[0:1] offset:2048
	global_load_dwordx4 v[108:111], v2, s[0:1] offset:3072
.Lp0r_nl_0:
	v_pk_mul_f32 v[10:11], v[48:49], v[48:49]
	v_pk_mul_f32 v[12:13], v[50:51], v[50:51]
	v_pk_fma_f32 v[10:11], v[52:53], v[52:53], v[10:11]
	v_pk_fma_f32 v[12:13], v[54:55], v[54:55], v[12:13]
	v_pk_fma_f32 v[10:11], v[56:57], v[56:57], v[10:11]
	v_pk_fma_f32 v[12:13], v[58:59], v[58:59], v[12:13]
	v_pk_fma_f32 v[10:11], v[60:61], v[60:61], v[10:11]
	v_pk_fma_f32 v[12:13], v[62:63], v[62:63], v[12:13]
	s_lshl_b32 s12, s62, 11
	v_pk_add_f32 v[10:11], v[10:11], v[12:13]
	s_add_u32 s12, s26, s12
	s_addc_u32 s13, s27, 0
	v_add_f32_e32 v6, v10, v11
	s_nop 1
	v_add_f32_dpp v6, v6, v6 quad_perm:[1,0,3,2] row_mask:0xf bank_mask:0xf
	s_nop 1
	v_add_f32_dpp v6, v6, v6 quad_perm:[2,3,0,1] row_mask:0xf bank_mask:0xf
	s_nop 1
	v_add_f32_dpp v6, v6, v6 row_half_mirror row_mask:0xf bank_mask:0xf
	s_nop 1
	v_add_f32_dpp v6, v6, v6 row_mirror row_mask:0xf bank_mask:0xf
	s_nop 1
	v_add_f32_dpp v6, v6, v6 row_bcast:15 row_mask:0xa bank_mask:0xf
	s_nop 1
	v_add_f32_dpp v6, v6, v6 row_bcast:31 row_mask:0xc bank_mask:0xf
	v_mov_b32_e32 v7, 0x358637bd
	s_nop 0
	v_fmamk_f32 v6, v6, 0x3a800000, v7
	s_nop 0
	v_rsq_f32_e32 v7, v6
	v_mul_f32_e32 v6, 0.5, v6
	s_nop 0
	v_mul_f32_e32 v6, v6, v7
	s_nop 0
	v_fma_f32 v6, -v6, v7, 0.5
	s_nop 0
	v_fma_f32 v7, v7, v6, v7
	s_nop 1
	v_readlane_b32 s4, v7, 63
	s_nop 3
	v_pk_mul_f32 v[48:49], v[48:49], s[4:5] op_sel_hi:[1,0]
	v_pk_mul_f32 v[50:51], v[50:51], s[4:5] op_sel_hi:[1,0]
	v_pk_mul_f32 v[52:53], v[52:53], s[4:5] op_sel_hi:[1,0]
	v_pk_mul_f32 v[54:55], v[54:55], s[4:5] op_sel_hi:[1,0]
	v_pk_mul_f32 v[56:57], v[56:57], s[4:5] op_sel_hi:[1,0]
	v_pk_mul_f32 v[58:59], v[58:59], s[4:5] op_sel_hi:[1,0]
; #define GAS __attribute__((address_space(1)))
; #define LAS __attribute__((address_space(3)))
; __device__ __forceinline__ unsigned pk2(float lo, float hi) { return pg8::cvt_pk_bf16_c(lo, hi); }
; __device__ __forceinline__ void p0_prologue(const Args& a, LAS unsigned char* lds, int vcu, int G, int tid, int lane, int wave) {
;     ...
;         for (int j = 0; j < 4; ++j) v[j] = v[j] * rstd * gv[j];
;         GAS unsigned long long* o8 = (GAS unsigned long long*)(XN + (size_t)m * DM) + lane;
; #pragma unroll
;         for (int j = 0; j < 4; ++j) o8[64 * j] = (unsigned long long)pk2(v[j].x, v[j].y) | ((unsigned long long)pk2(v[j].z, v[j].w) << 32);
;         float f[8];
; #pragma unroll
;         for (int h = 0; h < 8; ++h) { float acc = 0.f;
; #pragma unroll
;             for (int j = 0; j < 4; ++j) { const f32x4 w = *(const LAS f32x4*)(wf + h * 1024 + 256 * j + 4 * lane); acc += (v[j].x * w.x + v[j].y * w.y) + (v[j].z * w.z + v[j].w * w.w); }
	v_pk_mul_f32 v[60:61], v[60:61], s[4:5] op_sel_hi:[1,0]
	v_pk_mul_f32 v[62:63], v[62:63], s[4:5] op_sel_hi:[1,0]
	v_pk_mul_f32 v[48:49], v[48:49], v[112:113]
	v_pk_mul_f32 v[50:51], v[50:51], v[114:115]
	v_pk_mul_f32 v[52:53], v[52:53], v[116:117]
	v_pk_mul_f32 v[54:55], v[54:55], v[118:119]
	v_pk_mul_f32 v[56:57], v[56:57], v[120:121]
	v_pk_mul_f32 v[58:59], v[58:59], v[122:123]
	v_pk_mul_f32 v[60:61], v[60:61], v[124:125]
	v_pk_mul_f32 v[62:63], v[62:63], v[126:127]
	v_cvt_pk_bf16_f32 v38, v48, v49
	v_cvt_pk_bf16_f32 v39, v50, v51
	v_cvt_pk_bf16_f32 v40, v52, v53
	v_cvt_pk_bf16_f32 v41, v54, v55
	v_cvt_pk_bf16_f32 v42, v56, v57
	v_cvt_pk_bf16_f32 v43, v58, v59
	v_cvt_pk_bf16_f32 v44, v60, v61
	v_cvt_pk_bf16_f32 v45, v62, v63
	global_store_dwordx2 v3, v[38:39], s[12:13] offset:0
	global_store_dwordx2 v3, v[40:41], s[12:13] offset:512
	global_store_dwordx2 v3, v[42:43], s[12:13] offset:1024
	global_store_dwordx2 v3, v[44:45], s[12:13] offset:1536
	v_pk_mul_f32 v[16:17], v[48:49], v[128:129]
	v_pk_mul_f32 v[18:19], v[48:49], v[144:145]
	v_pk_mul_f32 v[20:21], v[48:49], v[160:161]
	v_pk_mul_f32 v[22:23], v[48:49], v[176:177]
	v_pk_mul_f32 v[24:25], v[48:49], v[192:193]
	v_pk_mul_f32 v[26:27], v[48:49], v[208:209]
	v_pk_mul_f32 v[28:29], v[48:49], v[224:225]
	v_pk_mul_f32 v[30:31], v[48:49], v[240:241]
	v_pk_fma_f32 v[16:17], v[50:51], v[130:131], v[16:17]
	v_pk_fma_f32 v[18:19], v[50:51], v[146:147], v[18:19]
	v_pk_fma_f32 v[20:21], v[50:51], v[162:163], v[20:21]
	v_pk_fma_f32 v[22:23], v[50:51], v[178:179], v[22:23]
	v_pk_fma_f32 v[24:25], v[50:51], v[194:195], v[24:25]
	v_pk_fma_f32 v[26:27], v[50:51], v[210:211], v[26:27]
	v_pk_fma_f32 v[28:29], v[50:51], v[226:227], v[28:29]
	v_pk_fma_f32 v[30:31], v[50:51], v[242:243], v[30:31]
	v_pk_fma_f32 v[16:17], v[52:53], v[132:133], v[16:17]
	v_pk_fma_f32 v[18:19], v[52:53], v[148:149], v[18:19]
	v_pk_fma_f32 v[20:21], v[52:53], v[164:165], v[20:21]
	v_pk_fma_f32 v[22:23], v[52:53], v[180:181], v[22:23]
	v_pk_fma_f32 v[24:25], v[52:53], v[196:197], v[24:25]
	v_pk_fma_f32 v[26:27], v[52:53], v[212:213], v[26:27]
	v_pk_fma_f32 v[28:29], v[52:53], v[228:229], v[28:29]
	v_pk_fma_f32 v[30:31], v[52:53], v[244:245], v[30:31]
	v_pk_fma_f32 v[16:17], v[54:55], v[134:135], v[16:17]
	v_pk_fma_f32 v[18:19], v[54:55], v[150:151], v[18:19]
	v_pk_fma_f32 v[20:21], v[54:55], v[166:167], v[20:21]
	v_pk_fma_f32 v[22:23], v[54:55], v[182:183], v[22:23]
	v_pk_fma_f32 v[24:25], v[54:55], v[198:199], v[24:25]
	v_pk_fma_f32 v[26:27], v[54:55], v[214:215], v[26:27]
	v_pk_fma_f32 v[28:29], v[54:55], v[230:231], v[28:29]
	v_pk_fma_f32 v[30:31], v[54:55], v[246:247], v[30:31]
	v_pk_fma_f32 v[16:17], v[56:57], v[136:137], v[16:17]
	v_pk_fma_f32 v[18:19], v[56:57], v[152:153], v[18:19]
	v_pk_fma_f32 v[20:21], v[56:57], v[168:169], v[20:21]
	v_pk_fma_f32 v[22:23], v[56:57], v[184:185], v[22:23]
	v_pk_fma_f32 v[24:25], v[56:57], v[200:201], v[24:25]
	v_pk_fma_f32 v[26:27], v[56:57], v[216:217], v[26:27]
	v_pk_fma_f32 v[28:29], v[56:57], v[232:233], v[28:29]
	v_pk_fma_f32 v[30:31], v[56:57], v[248:249], v[30:31]
	v_pk_fma_f32 v[16:17], v[58:59], v[138:139], v[16:17]
	v_pk_fma_f32 v[18:19], v[58:59], v[154:155], v[18:19]
	v_pk_fma_f32 v[20:21], v[58:59], v[170:171], v[20:21]
	v_pk_fma_f32 v[22:23], v[58:59], v[186:187], v[22:23]
	v_pk_fma_f32 v[24:25], v[58:59], v[202:203], v[24:25]
	v_pk_fma_f32 v[26:27], v[58:59], v[218:219], v[26:27]
	v_pk_fma_f32 v[28:29], v[58:59], v[234:235], v[28:29]
	v_pk_fma_f32 v[30:31], v[58:59], v[250:251], v[30:31]
	v_pk_fma_f32 v[16:17], v[60:61], v[140:141], v[16:17]
	v_pk_fma_f32 v[18:19], v[60:61], v[156:157], v[18:19]
	v_pk_fma_f32 v[20:21], v[60:61], v[172:173], v[20:21]
	v_pk_fma_f32 v[22:23], v[60:61], v[188:189], v[22:23]
	v_pk_fma_f32 v[24:25], v[60:61], v[204:205], v[24:25]
	v_pk_fma_f32 v[26:27], v[60:61], v[220:221], v[26:27]
	v_pk_fma_f32 v[28:29], v[60:61], v[236:237], v[28:29]
	v_pk_fma_f32 v[30:31], v[60:61], v[252:253], v[30:31]
	v_pk_fma_f32 v[16:17], v[62:63], v[142:143], v[16:17]
	v_pk_fma_f32 v[18:19], v[62:63], v[158:159], v[18:19]
	v_pk_fma_f32 v[20:21], v[62:63], v[174:175], v[20:21]
	v_pk_fma_f32 v[22:23], v[62:63], v[190:191], v[22:23]
	v_pk_fma_f32 v[24:25], v[62:63], v[206:207], v[24:25]
	v_pk_fma_f32 v[26:27], v[62:63], v[222:223], v[26:27]
	v_pk_fma_f32 v[28:29], v[62:63], v[238:239], v[28:29]
; #define LAS __attribute__((address_space(3)))
; __device__ __forceinline__ void p0_prologue(const Args& a, LAS unsigned char* lds, int vcu, int G, int tid, int lane, int wave) {
;     ...
;         for (int h = 0; h < 8; ++h) { float acc = 0.f;
; #pragma unroll
;             for (int j = 0; j < 4; ++j) { const f32x4 w = *(const LAS f32x4*)(wf + h * 1024 + 256 * j + 4 * lane); acc += (v[j].x * w.x + v[j].y * w.y) + (v[j].z * w.z + v[j].w * w.w); }
;             f[h] = wave_sum(acc); }
;         float fz = f[0];
; #pragma unroll
;         for (int h = 1; h < 8; ++h) fz = (lane == h) ? f[h] : fz;
	v_pk_fma_f32 v[30:31], v[62:63], v[254:255], v[30:31]
	v_add_f32_e32 v16, v16, v17
	v_add_f32_e32 v18, v18, v19
	v_add_f32_e32 v20, v20, v21
	v_add_f32_e32 v22, v22, v23
	v_add_f32_e32 v24, v24, v25
	v_add_f32_e32 v26, v26, v27
	v_add_f32_e32 v28, v28, v29
	v_add_f32_e32 v30, v30, v31
	v_add_f32_dpp v16, v16, v16 quad_perm:[1,0,3,2] row_mask:0xf bank_mask:0xf
	v_add_f32_dpp v18, v18, v18 quad_perm:[1,0,3,2] row_mask:0xf bank_mask:0xf
	v_add_f32_dpp v20, v20, v20 quad_perm:[1,0,3,2] row_mask:0xf bank_mask:0xf
	v_add_f32_dpp v22, v22, v22 quad_perm:[1,0,3,2] row_mask:0xf bank_mask:0xf
	v_add_f32_dpp v24, v24, v24 quad_perm:[1,0,3,2] row_mask:0xf bank_mask:0xf
	v_add_f32_dpp v26, v26, v26 quad_perm:[1,0,3,2] row_mask:0xf bank_mask:0xf
	v_add_f32_dpp v28, v28, v28 quad_perm:[1,0,3,2] row_mask:0xf bank_mask:0xf
	v_add_f32_dpp v30, v30, v30 quad_perm:[1,0,3,2] row_mask:0xf bank_mask:0xf
	v_add_f32_dpp v16, v16, v16 quad_perm:[2,3,0,1] row_mask:0xf bank_mask:0xf
	v_add_f32_dpp v18, v18, v18 quad_perm:[2,3,0,1] row_mask:0xf bank_mask:0xf
	v_add_f32_dpp v20, v20, v20 quad_perm:[2,3,0,1] row_mask:0xf bank_mask:0xf
	v_add_f32_dpp v22, v22, v22 quad_perm:[2,3,0,1] row_mask:0xf bank_mask:0xf
	v_add_f32_dpp v24, v24, v24 quad_perm:[2,3,0,1] row_mask:0xf bank_mask:0xf
	v_add_f32_dpp v26, v26, v26 quad_perm:[2,3,0,1] row_mask:0xf bank_mask:0xf
	v_add_f32_dpp v28, v28, v28 quad_perm:[2,3,0,1] row_mask:0xf bank_mask:0xf
	v_add_f32_dpp v30, v30, v30 quad_perm:[2,3,0,1] row_mask:0xf bank_mask:0xf
	v_add_f32_dpp v16, v16, v16 row_half_mirror row_mask:0xf bank_mask:0xf
	v_add_f32_dpp v18, v18, v18 row_half_mirror row_mask:0xf bank_mask:0xf
	v_add_f32_dpp v20, v20, v20 row_half_mirror row_mask:0xf bank_mask:0xf
	v_add_f32_dpp v22, v22, v22 row_half_mirror row_mask:0xf bank_mask:0xf
	v_add_f32_dpp v24, v24, v24 row_half_mirror row_mask:0xf bank_mask:0xf
	v_add_f32_dpp v26, v26, v26 row_half_mirror row_mask:0xf bank_mask:0xf
	v_add_f32_dpp v28, v28, v28 row_half_mirror row_mask:0xf bank_mask:0xf
	v_add_f32_dpp v30, v30, v30 row_half_mirror row_mask:0xf bank_mask:0xf
	v_add_f32_dpp v16, v16, v16 row_mirror row_mask:0xf bank_mask:0xf
	v_add_f32_dpp v18, v18, v18 row_mirror row_mask:0xf bank_mask:0xf
	v_add_f32_dpp v20, v20, v20 row_mirror row_mask:0xf bank_mask:0xf
	v_add_f32_dpp v22, v22, v22 row_mirror row_mask:0xf bank_mask:0xf
	v_add_f32_dpp v24, v24, v24 row_mirror row_mask:0xf bank_mask:0xf
	v_add_f32_dpp v26, v26, v26 row_mirror row_mask:0xf bank_mask:0xf
	v_add_f32_dpp v28, v28, v28 row_mirror row_mask:0xf bank_mask:0xf
	v_add_f32_dpp v30, v30, v30 row_mirror row_mask:0xf bank_mask:0xf
	v_add_f32_dpp v16, v16, v16 row_bcast:15 row_mask:0xa bank_mask:0xf
	v_add_f32_dpp v18, v18, v18 row_bcast:15 row_mask:0xa bank_mask:0xf
	v_add_f32_dpp v20, v20, v20 row_bcast:15 row_mask:0xa bank_mask:0xf
	v_add_f32_dpp v22, v22, v22 row_bcast:15 row_mask:0xa bank_mask:0xf
	v_add_f32_dpp v24, v24, v24 row_bcast:15 row_mask:0xa bank_mask:0xf
	v_add_f32_dpp v26, v26, v26 row_bcast:15 row_mask:0xa bank_mask:0xf
	v_add_f32_dpp v28, v28, v28 row_bcast:15 row_mask:0xa bank_mask:0xf
	v_add_f32_dpp v30, v30, v30 row_bcast:15 row_mask:0xa bank_mask:0xf
	v_add_f32_dpp v16, v16, v16 row_bcast:31 row_mask:0xc bank_mask:0xf
	v_add_f32_dpp v18, v18, v18 row_bcast:31 row_mask:0xc bank_mask:0xf
	v_add_f32_dpp v20, v20, v20 row_bcast:31 row_mask:0xc bank_mask:0xf
	v_add_f32_dpp v22, v22, v22 row_bcast:31 row_mask:0xc bank_mask:0xf
	v_add_f32_dpp v24, v24, v24 row_bcast:31 row_mask:0xc bank_mask:0xf
	v_add_f32_dpp v26, v26, v26 row_bcast:31 row_mask:0xc bank_mask:0xf
	v_add_f32_dpp v28, v28, v28 row_bcast:31 row_mask:0xc bank_mask:0xf
	v_add_f32_dpp v30, v30, v30 row_bcast:31 row_mask:0xc bank_mask:0xf
	s_nop 0
	v_readlane_b32 s14, v16, 63
	v_readlane_b32 s15, v18, 63
	v_readlane_b32 s16, v20, 63
	v_readlane_b32 s17, v22, 63
	v_readlane_b32 s18, v24, 63
	v_readlane_b32 s19, v26, 63
	v_readlane_b32 s46, v28, 63
	v_readlane_b32 s47, v30, 63
	s_nop 1
	v_writelane_b32 v4, s14, 0
	v_writelane_b32 v4, s15, 1
	v_writelane_b32 v4, s16, 2
	v_writelane_b32 v4, s17, 3
	v_writelane_b32 v4, s18, 4
	v_writelane_b32 v4, s19, 5
	v_writelane_b32 v4, s46, 6
	v_writelane_b32 v4, s47, 7
	s_mov_b32 s62, s8
	s_cmp_lt_i32 s8, 32768
	s_cbranch_scc1 .Lp0r_row1
	s_movk_i32 s6, 8
	s_branch .Lp0r_flush

; #define GAS __attribute__((address_space(1)))
; #define LAS __attribute__((address_space(3)))
; __device__ __forceinline__ unsigned pk2(float lo, float hi) { return pg8::cvt_pk_bf16_c(lo, hi); }
; __device__ __forceinline__ void p0_prologue(const Args& a, LAS unsigned char* lds, int vcu, int G, int tid, int lane, int wave) {
;     ...
;     for (int m = gw; m < T; m += NGW) {
;         f32x4 v[4]; float s2 = 0.f;
; #pragma unroll
;         for (int j = 0; j < 4; ++j) { v[j] = nv[j]; s2 += (v[j].x * v[j].x + v[j].y * v[j].y) + (v[j].z * v[j].z + v[j].w * v[j].w); }
;         if (m + NGW < T) { const GAS f32x4* xr = (const GAS f32x4*)(x + (size_t)(m + NGW) * DM) + lane;
; #pragma unroll
;             for (int j = 0; j < 4; ++j) nv[j] = xr[64 * j]; }
;         const float rstd = 1.0f / sqrtf(wave_sum(s2) * (1.f / DM) + EPS);
; #pragma unroll
;         for (int j = 0; j < 4; ++j) v[j] = v[j] * rstd * gv[j];
;         GAS unsigned long long* o8 = (GAS unsigned long long*)(XN + (size_t)m * DM) + lane;
; #pragma unroll
;         for (int j = 0; j < 4; ++j) o8[64 * j] = (unsigned long long)pk2(v[j].x, v[j].y) | ((unsigned long long)pk2(v[j].z, v[j].w) << 32);
;         float f[8];
; #pragma unroll
;         for (int h = 0; h < 8; ++h) { float acc = 0.f;
; #pragma unroll
;             for (int j = 0; j < 4; ++j) { const f32x4 w = *(const LAS f32x4*)(wf + h * 1024 + 256 * j + 4 * lane); acc += (v[j].x * w.x + v[j].y * w.y) + (v[j].z * w.z + v[j].w * w.w); }
.Lp0r_wd_1:
	s_cmp_lt_i32 s11, 32768
	s_cbranch_scc0 .Lp0r_nl_1
	s_lshl_b32 s0, s11, 12
	s_add_u32 s0, s36, s0
	s_addc_u32 s1, s37, 0
	global_load_dwordx4 v[48:51], v2, s[0:1] offset:0
	global_load_dwordx4 v[52:55], v2, s[0:1] offset:1024
	global_load_dwordx4 v[56:59], v2, s[0:1] offset:2048
	global_load_dwordx4 v[60:63], v2, s[0:1] offset:3072
.Lp0r_nl_1:
	v_pk_mul_f32 v[10:11], v[64:65], v[64:65]
	v_pk_mul_f32 v[12:13], v[66:67], v[66:67]
	v_pk_fma_f32 v[10:11], v[68:69], v[68:69], v[10:11]
	v_pk_fma_f32 v[12:13], v[70:71], v[70:71], v[12:13]
	v_pk_fma_f32 v[10:11], v[72:73], v[72:73], v[10:11]
	v_pk_fma_f32 v[12:13], v[74:75], v[74:75], v[12:13]
	v_pk_fma_f32 v[10:11], v[76:77], v[76:77], v[10:11]
	v_pk_fma_f32 v[12:13], v[78:79], v[78:79], v[12:13]
	s_lshl_b32 s12, s62, 11
	v_pk_add_f32 v[10:11], v[10:11], v[12:13]
	s_add_u32 s12, s26, s12
	s_addc_u32 s13, s27, 0
	v_add_f32_e32 v6, v10, v11
	s_nop 1
	v_add_f32_dpp v6, v6, v6 quad_perm:[1,0,3,2] row_mask:0xf bank_mask:0xf
	s_nop 1
	v_add_f32_dpp v6, v6, v6 quad_perm:[2,3,0,1] row_mask:0xf bank_mask:0xf
	s_nop 1
	v_add_f32_dpp v6, v6, v6 row_half_mirror row_mask:0xf bank_mask:0xf
	s_nop 1
	v_add_f32_dpp v6, v6, v6 row_mirror row_mask:0xf bank_mask:0xf
	s_nop 1
	v_add_f32_dpp v6, v6, v6 row_bcast:15 row_mask:0xa bank_mask:0xf
	s_nop 1
	v_add_f32_dpp v6, v6, v6 row_bcast:31 row_mask:0xc bank_mask:0xf
	v_mov_b32_e32 v7, 0x358637bd
	s_nop 0
	v_fmamk_f32 v6, v6, 0x3a800000, v7
	s_nop 0
	v_rsq_f32_e32 v7, v6
	v_mul_f32_e32 v6, 0.5, v6
	s_nop 0
	v_mul_f32_e32 v6, v6, v7
	s_nop 0
	v_fma_f32 v6, -v6, v7, 0.5
	s_nop 0
	v_fma_f32 v7, v7, v6, v7
	s_nop 1
	v_readlane_b32 s4, v7, 63
	s_nop 3
	v_pk_mul_f32 v[64:65], v[64:65], s[4:5] op_sel_hi:[1,0]
	v_pk_mul_f32 v[66:67], v[66:67], s[4:5] op_sel_hi:[1,0]
	v_pk_mul_f32 v[68:69], v[68:69], s[4:5] op_sel_hi:[1,0]
	v_pk_mul_f32 v[70:71], v[70:71], s[4:5] op_sel_hi:[1,0]
	v_pk_mul_f32 v[72:73], v[72:73], s[4:5] op_sel_hi:[1,0]
	v_pk_mul_f32 v[74:75], v[74:75], s[4:5] op_sel_hi:[1,0]
	v_pk_mul_f32 v[76:77], v[76:77], s[4:5] op_sel_hi:[1,0]
	v_pk_mul_f32 v[78:79], v[78:79], s[4:5] op_sel_hi:[1,0]
	v_pk_mul_f32 v[64:65], v[64:65], v[112:113]
	v_pk_mul_f32 v[66:67], v[66:67], v[114:115]
	v_pk_mul_f32 v[68:69], v[68:69], v[116:117]
	v_pk_mul_f32 v[70:71], v[70:71], v[118:119]
	v_pk_mul_f32 v[72:73], v[72:73], v[120:121]
	v_pk_mul_f32 v[74:75], v[74:75], v[122:123]
	v_pk_mul_f32 v[76:77], v[76:77], v[124:125]
	v_pk_mul_f32 v[78:79], v[78:79], v[126:127]
	v_cvt_pk_bf16_f32 v38, v64, v65
	v_cvt_pk_bf16_f32 v39, v66, v67
	v_cvt_pk_bf16_f32 v40, v68, v69
	v_cvt_pk_bf16_f32 v41, v70, v71
	v_cvt_pk_bf16_f32 v42, v72, v73
	v_cvt_pk_bf16_f32 v43, v74, v75
	v_cvt_pk_bf16_f32 v44, v76, v77
	v_cvt_pk_bf16_f32 v45, v78, v79
	global_store_dwordx2 v3, v[38:39], s[12:13] offset:0
	global_store_dwordx2 v3, v[40:41], s[12:13] offset:512
	global_store_dwordx2 v3, v[42:43], s[12:13] offset:1024
	global_store_dwordx2 v3, v[44:45], s[12:13] offset:1536
	v_pk_mul_f32 v[16:17], v[64:65], v[128:129]
	v_pk_mul_f32 v[18:19], v[64:65], v[144:145]
	v_pk_mul_f32 v[20:21], v[64:65], v[160:161]
	v_pk_mul_f32 v[22:23], v[64:65], v[176:177]
	v_pk_mul_f32 v[24:25], v[64:65], v[192:193]
	v_pk_mul_f32 v[26:27], v[64:65], v[208:209]
	v_pk_mul_f32 v[28:29], v[64:65], v[224:225]
	v_pk_mul_f32 v[30:31], v[64:65], v[240:241]
	v_pk_fma_f32 v[16:17], v[66:67], v[130:131], v[16:17]
	v_pk_fma_f32 v[18:19], v[66:67], v[146:147], v[18:19]
	v_pk_fma_f32 v[20:21], v[66:67], v[162:163], v[20:21]
	v_pk_fma_f32 v[22:23], v[66:67], v[178:179], v[22:23]
	v_pk_fma_f32 v[24:25], v[66:67], v[194:195], v[24:25]
	v_pk_fma_f32 v[26:27], v[66:67], v[210:211], v[26:27]
	v_pk_fma_f32 v[28:29], v[66:67], v[226:227], v[28:29]
	v_pk_fma_f32 v[30:31], v[66:67], v[242:243], v[30:31]
	v_pk_fma_f32 v[16:17], v[68:69], v[132:133], v[16:17]
	v_pk_fma_f32 v[18:19], v[68:69], v[148:149], v[18:19]
	v_pk_fma_f32 v[20:21], v[68:69], v[164:165], v[20:21]
	v_pk_fma_f32 v[22:23], v[68:69], v[180:181], v[22:23]
	v_pk_fma_f32 v[24:25], v[68:69], v[196:197], v[24:25]
	v_pk_fma_f32 v[26:27], v[68:69], v[212:213], v[26:27]
	v_pk_fma_f32 v[28:29], v[68:69], v[228:229], v[28:29]
	v_pk_fma_f32 v[30:31], v[68:69], v[244:245], v[30:31]
	v_pk_fma_f32 v[16:17], v[70:71], v[134:135], v[16:17]
	v_pk_fma_f32 v[18:19], v[70:71], v[150:151], v[18:19]
	v_pk_fma_f32 v[20:21], v[70:71], v[166:167], v[20:21]
	v_pk_fma_f32 v[22:23], v[70:71], v[182:183], v[22:23]
	v_pk_fma_f32 v[24:25], v[70:71], v[198:199], v[24:25]
	v_pk_fma_f32 v[26:27], v[70:71], v[214:215], v[26:27]
	v_pk_fma_f32 v[28:29], v[70:71], v[230:231], v[28:29]
	v_pk_fma_f32 v[30:31], v[70:71], v[246:247], v[30:31]
	v_pk_fma_f32 v[16:17], v[72:73], v[136:137], v[16:17]
	v_pk_fma_f32 v[18:19], v[72:73], v[152:153], v[18:19]
	v_pk_fma_f32 v[20:21], v[72:73], v[168:169], v[20:21]
	v_pk_fma_f32 v[22:23], v[72:73], v[184:185], v[22:23]
	v_pk_fma_f32 v[24:25], v[72:73], v[200:201], v[24:25]
	v_pk_fma_f32 v[26:27], v[72:73], v[216:217], v[26:27]
	v_pk_fma_f32 v[28:29], v[72:73], v[232:233], v[28:29]
	v_pk_fma_f32 v[30:31], v[72:73], v[248:249], v[30:31]
	v_pk_fma_f32 v[16:17], v[74:75], v[138:139], v[16:17]
	v_pk_fma_f32 v[18:19], v[74:75], v[154:155], v[18:19]
	v_pk_fma_f32 v[20:21], v[74:75], v[170:171], v[20:21]
	v_pk_fma_f32 v[22:23], v[74:75], v[186:187], v[22:23]
; #define LAS __attribute__((address_space(3)))
; __device__ __forceinline__ void p0_prologue(const Args& a, LAS unsigned char* lds, int vcu, int G, int tid, int lane, int wave) {
;     ...
;         for (int h = 0; h < 8; ++h) { float acc = 0.f;
; #pragma unroll
;             for (int j = 0; j < 4; ++j) { const f32x4 w = *(const LAS f32x4*)(wf + h * 1024 + 256 * j + 4 * lane); acc += (v[j].x * w.x + v[j].y * w.y) + (v[j].z * w.z + v[j].w * w.w); }
;             f[h] = wave_sum(acc); }
;         float fz = f[0];
; #pragma unroll
;         for (int h = 1; h < 8; ++h) fz = (lane == h) ? f[h] : fz;
	v_pk_fma_f32 v[24:25], v[74:75], v[202:203], v[24:25]
	v_pk_fma_f32 v[26:27], v[74:75], v[218:219], v[26:27]
	v_pk_fma_f32 v[28:29], v[74:75], v[234:235], v[28:29]
	v_pk_fma_f32 v[30:31], v[74:75], v[250:251], v[30:31]
	v_pk_fma_f32 v[16:17], v[76:77], v[140:141], v[16:17]
	v_pk_fma_f32 v[18:19], v[76:77], v[156:157], v[18:19]
	v_pk_fma_f32 v[20:21], v[76:77], v[172:173], v[20:21]
	v_pk_fma_f32 v[22:23], v[76:77], v[188:189], v[22:23]
	v_pk_fma_f32 v[24:25], v[76:77], v[204:205], v[24:25]
	v_pk_fma_f32 v[26:27], v[76:77], v[220:221], v[26:27]
	v_pk_fma_f32 v[28:29], v[76:77], v[236:237], v[28:29]
	v_pk_fma_f32 v[30:31], v[76:77], v[252:253], v[30:31]
	v_pk_fma_f32 v[16:17], v[78:79], v[142:143], v[16:17]
	v_pk_fma_f32 v[18:19], v[78:79], v[158:159], v[18:19]
	v_pk_fma_f32 v[20:21], v[78:79], v[174:175], v[20:21]
	v_pk_fma_f32 v[22:23], v[78:79], v[190:191], v[22:23]
	v_pk_fma_f32 v[24:25], v[78:79], v[206:207], v[24:25]
	v_pk_fma_f32 v[26:27], v[78:79], v[222:223], v[26:27]
	v_pk_fma_f32 v[28:29], v[78:79], v[238:239], v[28:29]
	v_pk_fma_f32 v[30:31], v[78:79], v[254:255], v[30:31]
	v_add_f32_e32 v16, v16, v17
	v_add_f32_e32 v18, v18, v19
	v_add_f32_e32 v20, v20, v21
	v_add_f32_e32 v22, v22, v23
	v_add_f32_e32 v24, v24, v25
	v_add_f32_e32 v26, v26, v27
	v_add_f32_e32 v28, v28, v29
	v_add_f32_e32 v30, v30, v31
	v_add_f32_dpp v16, v16, v16 quad_perm:[1,0,3,2] row_mask:0xf bank_mask:0xf
	v_add_f32_dpp v18, v18, v18 quad_perm:[1,0,3,2] row_mask:0xf bank_mask:0xf
	v_add_f32_dpp v20, v20, v20 quad_perm:[1,0,3,2] row_mask:0xf bank_mask:0xf
	v_add_f32_dpp v22, v22, v22 quad_perm:[1,0,3,2] row_mask:0xf bank_mask:0xf
	v_add_f32_dpp v24, v24, v24 quad_perm:[1,0,3,2] row_mask:0xf bank_mask:0xf
	v_add_f32_dpp v26, v26, v26 quad_perm:[1,0,3,2] row_mask:0xf bank_mask:0xf
	v_add_f32_dpp v28, v28, v28 quad_perm:[1,0,3,2] row_mask:0xf bank_mask:0xf
	v_add_f32_dpp v30, v30, v30 quad_perm:[1,0,3,2] row_mask:0xf bank_mask:0xf
	v_add_f32_dpp v16, v16, v16 quad_perm:[2,3,0,1] row_mask:0xf bank_mask:0xf
	v_add_f32_dpp v18, v18, v18 quad_perm:[2,3,0,1] row_mask:0xf bank_mask:0xf
	v_add_f32_dpp v20, v20, v20 quad_perm:[2,3,0,1] row_mask:0xf bank_mask:0xf
	v_add_f32_dpp v22, v22, v22 quad_perm:[2,3,0,1] row_mask:0xf bank_mask:0xf
	v_add_f32_dpp v24, v24, v24 quad_perm:[2,3,0,1] row_mask:0xf bank_mask:0xf
	v_add_f32_dpp v26, v26, v26 quad_perm:[2,3,0,1] row_mask:0xf bank_mask:0xf
	v_add_f32_dpp v28, v28, v28 quad_perm:[2,3,0,1] row_mask:0xf bank_mask:0xf
	v_add_f32_dpp v30, v30, v30 quad_perm:[2,3,0,1] row_mask:0xf bank_mask:0xf
	v_add_f32_dpp v16, v16, v16 row_half_mirror row_mask:0xf bank_mask:0xf
	v_add_f32_dpp v18, v18, v18 row_half_mirror row_mask:0xf bank_mask:0xf
	v_add_f32_dpp v20, v20, v20 row_half_mirror row_mask:0xf bank_mask:0xf
	v_add_f32_dpp v22, v22, v22 row_half_mirror row_mask:0xf bank_mask:0xf
	v_add_f32_dpp v24, v24, v24 row_half_mirror row_mask:0xf bank_mask:0xf
	v_add_f32_dpp v26, v26, v26 row_half_mirror row_mask:0xf bank_mask:0xf
	v_add_f32_dpp v28, v28, v28 row_half_mirror row_mask:0xf bank_mask:0xf
	v_add_f32_dpp v30, v30, v30 row_half_mirror row_mask:0xf bank_mask:0xf
	v_add_f32_dpp v16, v16, v16 row_mirror row_mask:0xf bank_mask:0xf
	v_add_f32_dpp v18, v18, v18 row_mirror row_mask:0xf bank_mask:0xf
	v_add_f32_dpp v20, v20, v20 row_mirror row_mask:0xf bank_mask:0xf
	v_add_f32_dpp v22, v22, v22 row_mirror row_mask:0xf bank_mask:0xf
	v_add_f32_dpp v24, v24, v24 row_mirror row_mask:0xf bank_mask:0xf
	v_add_f32_dpp v26, v26, v26 row_mirror row_mask:0xf bank_mask:0xf
	v_add_f32_dpp v28, v28, v28 row_mirror row_mask:0xf bank_mask:0xf
	v_add_f32_dpp v30, v30, v30 row_mirror row_mask:0xf bank_mask:0xf
	v_add_f32_dpp v16, v16, v16 row_bcast:15 row_mask:0xa bank_mask:0xf
	v_add_f32_dpp v18, v18, v18 row_bcast:15 row_mask:0xa bank_mask:0xf
	v_add_f32_dpp v20, v20, v20 row_bcast:15 row_mask:0xa bank_mask:0xf
	v_add_f32_dpp v22, v22, v22 row_bcast:15 row_mask:0xa bank_mask:0xf
	v_add_f32_dpp v24, v24, v24 row_bcast:15 row_mask:0xa bank_mask:0xf
	v_add_f32_dpp v26, v26, v26 row_bcast:15 row_mask:0xa bank_mask:0xf
	v_add_f32_dpp v28, v28, v28 row_bcast:15 row_mask:0xa bank_mask:0xf
	v_add_f32_dpp v30, v30, v30 row_bcast:15 row_mask:0xa bank_mask:0xf
	v_add_f32_dpp v16, v16, v16 row_bcast:31 row_mask:0xc bank_mask:0xf
	v_add_f32_dpp v18, v18, v18 row_bcast:31 row_mask:0xc bank_mask:0xf
	v_add_f32_dpp v20, v20, v20 row_bcast:31 row_mask:0xc bank_mask:0xf
	v_add_f32_dpp v22, v22, v22 row_bcast:31 row_mask:0xc bank_mask:0xf
	v_add_f32_dpp v24, v24, v24 row_bcast:31 row_mask:0xc bank_mask:0xf
	v_add_f32_dpp v26, v26, v26 row_bcast:31 row_mask:0xc bank_mask:0xf
	v_add_f32_dpp v28, v28, v28 row_bcast:31 row_mask:0xc bank_mask:0xf
	v_add_f32_dpp v30, v30, v30 row_bcast:31 row_mask:0xc bank_mask:0xf
	s_nop 0
	v_readlane_b32 s14, v16, 63
	v_readlane_b32 s15, v18, 63
	v_readlane_b32 s16, v20, 63
	v_readlane_b32 s17, v22, 63
	v_readlane_b32 s18, v24, 63
	v_readlane_b32 s19, v26, 63
	v_readlane_b32 s46, v28, 63
	v_readlane_b32 s47, v30, 63
	s_nop 1
	v_writelane_b32 v4, s14, 8
	v_writelane_b32 v4, s15, 9
	v_writelane_b32 v4, s16, 10
	v_writelane_b32 v4, s17, 11
	v_writelane_b32 v4, s18, 12
	v_writelane_b32 v4, s19, 13
	v_writelane_b32 v4, s46, 14
	v_writelane_b32 v4, s47, 15
	s_mov_b32 s62, s8
	s_cmp_lt_i32 s8, 32768
	s_cbranch_scc1 .Lp0r_row2
	s_movk_i32 s6, 16
	s_branch .Lp0r_flush

; #define GAS __attribute__((address_space(1)))
; #define LAS __attribute__((address_space(3)))
; __device__ __forceinline__ unsigned pk2(float lo, float hi) { return pg8::cvt_pk_bf16_c(lo, hi); }
; __device__ __forceinline__ void p0_prologue(const Args& a, LAS unsigned char* lds, int vcu, int G, int tid, int lane, int wave) {
;     ...
;     for (int m = gw; m < T; m += NGW) {
;         f32x4 v[4]; float s2 = 0.f;
; #pragma unroll
;         for (int j = 0; j < 4; ++j) { v[j] = nv[j]; s2 += (v[j].x * v[j].x + v[j].y * v[j].y) + (v[j].z * v[j].z + v[j].w * v[j].w); }
;         if (m + NGW < T) { const GAS f32x4* xr = (const GAS f32x4*)(x + (size_t)(m + NGW) * DM) + lane;
; #pragma unroll
;             for (int j = 0; j < 4; ++j) nv[j] = xr[64 * j]; }
;         const float rstd = 1.0f / sqrtf(wave_sum(s2) * (1.f / DM) + EPS);
; #pragma unroll
;         for (int j = 0; j < 4; ++j) v[j] = v[j] * rstd * gv[j];
;         GAS unsigned long long* o8 = (GAS unsigned long long*)(XN + (size_t)m * DM) + lane;
; #pragma unroll
;         for (int j = 0; j < 4; ++j) o8[64 * j] = (unsigned long long)pk2(v[j].x, v[j].y) | ((unsigned long long)pk2(v[j].z, v[j].w) << 32);
;         float f[8];
; #pragma unroll
;         for (int h = 0; h < 8; ++h) { float acc = 0.f;
; #pragma unroll
;             for (int j = 0; j < 4; ++j) { const f32x4 w = *(const LAS f32x4*)(wf + h * 1024 + 256 * j + 4 * lane); acc += (v[j].x * w.x + v[j].y * w.y) + (v[j].z * w.z + v[j].w * w.w); }
.Lp0r_wd_2:
	s_cmp_lt_i32 s11, 32768
	s_cbranch_scc0 .Lp0r_nl_2
	s_lshl_b32 s0, s11, 12
	s_add_u32 s0, s36, s0
	s_addc_u32 s1, s37, 0
	global_load_dwordx4 v[64:67], v2, s[0:1] offset:0
	global_load_dwordx4 v[68:71], v2, s[0:1] offset:1024
	global_load_dwordx4 v[72:75], v2, s[0:1] offset:2048
	global_load_dwordx4 v[76:79], v2, s[0:1] offset:3072
.Lp0r_nl_2:
	v_pk_mul_f32 v[10:11], v[80:81], v[80:81]
	v_pk_mul_f32 v[12:13], v[82:83], v[82:83]
	v_pk_fma_f32 v[10:11], v[84:85], v[84:85], v[10:11]
	v_pk_fma_f32 v[12:13], v[86:87], v[86:87], v[12:13]
	v_pk_fma_f32 v[10:11], v[88:89], v[88:89], v[10:11]
	v_pk_fma_f32 v[12:13], v[90:91], v[90:91], v[12:13]
	v_pk_fma_f32 v[10:11], v[92:93], v[92:93], v[10:11]
	v_pk_fma_f32 v[12:13], v[94:95], v[94:95], v[12:13]
	s_lshl_b32 s12, s62, 11
	v_pk_add_f32 v[10:11], v[10:11], v[12:13]
	s_add_u32 s12, s26, s12
	s_addc_u32 s13, s27, 0
	v_add_f32_e32 v6, v10, v11
	s_nop 1
	v_add_f32_dpp v6, v6, v6 quad_perm:[1,0,3,2] row_mask:0xf bank_mask:0xf
	s_nop 1
	v_add_f32_dpp v6, v6, v6 quad_perm:[2,3,0,1] row_mask:0xf bank_mask:0xf
	s_nop 1
	v_add_f32_dpp v6, v6, v6 row_half_mirror row_mask:0xf bank_mask:0xf
	s_nop 1
	v_add_f32_dpp v6, v6, v6 row_mirror row_mask:0xf bank_mask:0xf
	s_nop 1
	v_add_f32_dpp v6, v6, v6 row_bcast:15 row_mask:0xa bank_mask:0xf
	s_nop 1
	v_add_f32_dpp v6, v6, v6 row_bcast:31 row_mask:0xc bank_mask:0xf
	v_mov_b32_e32 v7, 0x358637bd
	s_nop 0
	v_fmamk_f32 v6, v6, 0x3a800000, v7
	s_nop 0
	v_rsq_f32_e32 v7, v6
	v_mul_f32_e32 v6, 0.5, v6
	s_nop 0
	v_mul_f32_e32 v6, v6, v7
	s_nop 0
	v_fma_f32 v6, -v6, v7, 0.5
	s_nop 0
	v_fma_f32 v7, v7, v6, v7
	s_nop 1
	v_readlane_b32 s4, v7, 63
	s_nop 3
	v_pk_mul_f32 v[80:81], v[80:81], s[4:5] op_sel_hi:[1,0]
	v_pk_mul_f32 v[82:83], v[82:83], s[4:5] op_sel_hi:[1,0]
	v_pk_mul_f32 v[84:85], v[84:85], s[4:5] op_sel_hi:[1,0]
	v_pk_mul_f32 v[86:87], v[86:87], s[4:5] op_sel_hi:[1,0]
	v_pk_mul_f32 v[88:89], v[88:89], s[4:5] op_sel_hi:[1,0]
	v_pk_mul_f32 v[90:91], v[90:91], s[4:5] op_sel_hi:[1,0]
	v_pk_mul_f32 v[92:93], v[92:93], s[4:5] op_sel_hi:[1,0]
	v_pk_mul_f32 v[94:95], v[94:95], s[4:5] op_sel_hi:[1,0]
	v_pk_mul_f32 v[80:81], v[80:81], v[112:113]
	v_pk_mul_f32 v[82:83], v[82:83], v[114:115]
	v_pk_mul_f32 v[84:85], v[84:85], v[116:117]
	v_pk_mul_f32 v[86:87], v[86:87], v[118:119]
	v_pk_mul_f32 v[88:89], v[88:89], v[120:121]
	v_pk_mul_f32 v[90:91], v[90:91], v[122:123]
	v_pk_mul_f32 v[92:93], v[92:93], v[124:125]
	v_pk_mul_f32 v[94:95], v[94:95], v[126:127]
	v_cvt_pk_bf16_f32 v38, v80, v81
	v_cvt_pk_bf16_f32 v39, v82, v83
	v_cvt_pk_bf16_f32 v40, v84, v85
	v_cvt_pk_bf16_f32 v41, v86, v87
	v_cvt_pk_bf16_f32 v42, v88, v89
	v_cvt_pk_bf16_f32 v43, v90, v91
	v_cvt_pk_bf16_f32 v44, v92, v93
	v_cvt_pk_bf16_f32 v45, v94, v95
	global_store_dwordx2 v3, v[38:39], s[12:13] offset:0
	global_store_dwordx2 v3, v[40:41], s[12:13] offset:512
	global_store_dwordx2 v3, v[42:43], s[12:13] offset:1024
	global_store_dwordx2 v3, v[44:45], s[12:13] offset:1536
	v_pk_mul_f32 v[16:17], v[80:81], v[128:129]
	v_pk_mul_f32 v[18:19], v[80:81], v[144:145]
	v_pk_mul_f32 v[20:21], v[80:81], v[160:161]
	v_pk_mul_f32 v[22:23], v[80:81], v[176:177]
	v_pk_mul_f32 v[24:25], v[80:81], v[192:193]
	v_pk_mul_f32 v[26:27], v[80:81], v[208:209]
	v_pk_mul_f32 v[28:29], v[80:81], v[224:225]
	v_pk_mul_f32 v[30:31], v[80:81], v[240:241]
	v_pk_fma_f32 v[16:17], v[82:83], v[130:131], v[16:17]
	v_pk_fma_f32 v[18:19], v[82:83], v[146:147], v[18:19]
	v_pk_fma_f32 v[20:21], v[82:83], v[162:163], v[20:21]
	v_pk_fma_f32 v[22:23], v[82:83], v[178:179], v[22:23]
	v_pk_fma_f32 v[24:25], v[82:83], v[194:195], v[24:25]
	v_pk_fma_f32 v[26:27], v[82:83], v[210:211], v[26:27]
	v_pk_fma_f32 v[28:29], v[82:83], v[226:227], v[28:29]
	v_pk_fma_f32 v[30:31], v[82:83], v[242:243], v[30:31]
	v_pk_fma_f32 v[16:17], v[84:85], v[132:133], v[16:17]
	v_pk_fma_f32 v[18:19], v[84:85], v[148:149], v[18:19]
	v_pk_fma_f32 v[20:21], v[84:85], v[164:165], v[20:21]
	v_pk_fma_f32 v[22:23], v[84:85], v[180:181], v[22:23]
	v_pk_fma_f32 v[24:25], v[84:85], v[196:197], v[24:25]
	v_pk_fma_f32 v[26:27], v[84:85], v[212:213], v[26:27]
	v_pk_fma_f32 v[28:29], v[84:85], v[228:229], v[28:29]
	v_pk_fma_f32 v[30:31], v[84:85], v[244:245], v[30:31]
	v_pk_fma_f32 v[16:17], v[86:87], v[134:135], v[16:17]
	v_pk_fma_f32 v[18:19], v[86:87], v[150:151], v[18:19]
	v_pk_fma_f32 v[20:21], v[86:87], v[166:167], v[20:21]
	v_pk_fma_f32 v[22:23], v[86:87], v[182:183], v[22:23]
	v_pk_fma_f32 v[24:25], v[86:87], v[198:199], v[24:25]
	v_pk_fma_f32 v[26:27], v[86:87], v[214:215], v[26:27]
	v_pk_fma_f32 v[28:29], v[86:87], v[230:231], v[28:29]
	v_pk_fma_f32 v[30:31], v[86:87], v[246:247], v[30:31]
	v_pk_fma_f32 v[16:17], v[88:89], v[136:137], v[16:17]
	v_pk_fma_f32 v[18:19], v[88:89], v[152:153], v[18:19]
	v_pk_fma_f32 v[20:21], v[88:89], v[168:169], v[20:21]
	v_pk_fma_f32 v[22:23], v[88:89], v[184:185], v[22:23]
	v_pk_fma_f32 v[24:25], v[88:89], v[200:201], v[24:25]
	v_pk_fma_f32 v[26:27], v[88:89], v[216:217], v[26:27]
	v_pk_fma_f32 v[28:29], v[88:89], v[232:233], v[28:29]
	v_pk_fma_f32 v[30:31], v[88:89], v[248:249], v[30:31]
	v_pk_fma_f32 v[16:17], v[90:91], v[138:139], v[16:17]
	v_pk_fma_f32 v[18:19], v[90:91], v[154:155], v[18:19]
	v_pk_fma_f32 v[20:21], v[90:91], v[170:171], v[20:21]
	v_pk_fma_f32 v[22:23], v[90:91], v[186:187], v[22:23]
; #define LAS __attribute__((address_space(3)))
; __device__ __forceinline__ void p0_prologue(const Args& a, LAS unsigned char* lds, int vcu, int G, int tid, int lane, int wave) {
;     ...
;         for (int h = 0; h < 8; ++h) { float acc = 0.f;
; #pragma unroll
;             for (int j = 0; j < 4; ++j) { const f32x4 w = *(const LAS f32x4*)(wf + h * 1024 + 256 * j + 4 * lane); acc += (v[j].x * w.x + v[j].y * w.y) + (v[j].z * w.z + v[j].w * w.w); }
;             f[h] = wave_sum(acc); }
;         float fz = f[0];
; #pragma unroll
;         for (int h = 1; h < 8; ++h) fz = (lane == h) ? f[h] : fz;
	v_pk_fma_f32 v[24:25], v[90:91], v[202:203], v[24:25]
	v_pk_fma_f32 v[26:27], v[90:91], v[218:219], v[26:27]
	v_pk_fma_f32 v[28:29], v[90:91], v[234:235], v[28:29]
	v_pk_fma_f32 v[30:31], v[90:91], v[250:251], v[30:31]
	v_pk_fma_f32 v[16:17], v[92:93], v[140:141], v[16:17]
	v_pk_fma_f32 v[18:19], v[92:93], v[156:157], v[18:19]
	v_pk_fma_f32 v[20:21], v[92:93], v[172:173], v[20:21]
	v_pk_fma_f32 v[22:23], v[92:93], v[188:189], v[22:23]
	v_pk_fma_f32 v[24:25], v[92:93], v[204:205], v[24:25]
	v_pk_fma_f32 v[26:27], v[92:93], v[220:221], v[26:27]
	v_pk_fma_f32 v[28:29], v[92:93], v[236:237], v[28:29]
	v_pk_fma_f32 v[30:31], v[92:93], v[252:253], v[30:31]
	v_pk_fma_f32 v[16:17], v[94:95], v[142:143], v[16:17]
	v_pk_fma_f32 v[18:19], v[94:95], v[158:159], v[18:19]
	v_pk_fma_f32 v[20:21], v[94:95], v[174:175], v[20:21]
	v_pk_fma_f32 v[22:23], v[94:95], v[190:191], v[22:23]
	v_pk_fma_f32 v[24:25], v[94:95], v[206:207], v[24:25]
	v_pk_fma_f32 v[26:27], v[94:95], v[222:223], v[26:27]
	v_pk_fma_f32 v[28:29], v[94:95], v[238:239], v[28:29]
	v_pk_fma_f32 v[30:31], v[94:95], v[254:255], v[30:31]
	v_add_f32_e32 v16, v16, v17
	v_add_f32_e32 v18, v18, v19
	v_add_f32_e32 v20, v20, v21
	v_add_f32_e32 v22, v22, v23
	v_add_f32_e32 v24, v24, v25
	v_add_f32_e32 v26, v26, v27
	v_add_f32_e32 v28, v28, v29
	v_add_f32_e32 v30, v30, v31
	v_add_f32_dpp v16, v16, v16 quad_perm:[1,0,3,2] row_mask:0xf bank_mask:0xf
	v_add_f32_dpp v18, v18, v18 quad_perm:[1,0,3,2] row_mask:0xf bank_mask:0xf
	v_add_f32_dpp v20, v20, v20 quad_perm:[1,0,3,2] row_mask:0xf bank_mask:0xf
	v_add_f32_dpp v22, v22, v22 quad_perm:[1,0,3,2] row_mask:0xf bank_mask:0xf
	v_add_f32_dpp v24, v24, v24 quad_perm:[1,0,3,2] row_mask:0xf bank_mask:0xf
	v_add_f32_dpp v26, v26, v26 quad_perm:[1,0,3,2] row_mask:0xf bank_mask:0xf
	v_add_f32_dpp v28, v28, v28 quad_perm:[1,0,3,2] row_mask:0xf bank_mask:0xf
	v_add_f32_dpp v30, v30, v30 quad_perm:[1,0,3,2] row_mask:0xf bank_mask:0xf
	v_add_f32_dpp v16, v16, v16 quad_perm:[2,3,0,1] row_mask:0xf bank_mask:0xf
	v_add_f32_dpp v18, v18, v18 quad_perm:[2,3,0,1] row_mask:0xf bank_mask:0xf
	v_add_f32_dpp v20, v20, v20 quad_perm:[2,3,0,1] row_mask:0xf bank_mask:0xf
	v_add_f32_dpp v22, v22, v22 quad_perm:[2,3,0,1] row_mask:0xf bank_mask:0xf
	v_add_f32_dpp v24, v24, v24 quad_perm:[2,3,0,1] row_mask:0xf bank_mask:0xf
	v_add_f32_dpp v26, v26, v26 quad_perm:[2,3,0,1] row_mask:0xf bank_mask:0xf
	v_add_f32_dpp v28, v28, v28 quad_perm:[2,3,0,1] row_mask:0xf bank_mask:0xf
	v_add_f32_dpp v30, v30, v30 quad_perm:[2,3,0,1] row_mask:0xf bank_mask:0xf
	v_add_f32_dpp v16, v16, v16 row_half_mirror row_mask:0xf bank_mask:0xf
	v_add_f32_dpp v18, v18, v18 row_half_mirror row_mask:0xf bank_mask:0xf
	v_add_f32_dpp v20, v20, v20 row_half_mirror row_mask:0xf bank_mask:0xf
	v_add_f32_dpp v22, v22, v22 row_half_mirror row_mask:0xf bank_mask:0xf
	v_add_f32_dpp v24, v24, v24 row_half_mirror row_mask:0xf bank_mask:0xf
	v_add_f32_dpp v26, v26, v26 row_half_mirror row_mask:0xf bank_mask:0xf
	v_add_f32_dpp v28, v28, v28 row_half_mirror row_mask:0xf bank_mask:0xf
	v_add_f32_dpp v30, v30, v30 row_half_mirror row_mask:0xf bank_mask:0xf
	v_add_f32_dpp v16, v16, v16 row_mirror row_mask:0xf bank_mask:0xf
	v_add_f32_dpp v18, v18, v18 row_mirror row_mask:0xf bank_mask:0xf
	v_add_f32_dpp v20, v20, v20 row_mirror row_mask:0xf bank_mask:0xf
	v_add_f32_dpp v22, v22, v22 row_mirror row_mask:0xf bank_mask:0xf
	v_add_f32_dpp v24, v24, v24 row_mirror row_mask:0xf bank_mask:0xf
	v_add_f32_dpp v26, v26, v26 row_mirror row_mask:0xf bank_mask:0xf
	v_add_f32_dpp v28, v28, v28 row_mirror row_mask:0xf bank_mask:0xf
	v_add_f32_dpp v30, v30, v30 row_mirror row_mask:0xf bank_mask:0xf
	v_add_f32_dpp v16, v16, v16 row_bcast:15 row_mask:0xa bank_mask:0xf
	v_add_f32_dpp v18, v18, v18 row_bcast:15 row_mask:0xa bank_mask:0xf
	v_add_f32_dpp v20, v20, v20 row_bcast:15 row_mask:0xa bank_mask:0xf
	v_add_f32_dpp v22, v22, v22 row_bcast:15 row_mask:0xa bank_mask:0xf
	v_add_f32_dpp v24, v24, v24 row_bcast:15 row_mask:0xa bank_mask:0xf
	v_add_f32_dpp v26, v26, v26 row_bcast:15 row_mask:0xa bank_mask:0xf
	v_add_f32_dpp v28, v28, v28 row_bcast:15 row_mask:0xa bank_mask:0xf
	v_add_f32_dpp v30, v30, v30 row_bcast:15 row_mask:0xa bank_mask:0xf
	v_add_f32_dpp v16, v16, v16 row_bcast:31 row_mask:0xc bank_mask:0xf
	v_add_f32_dpp v18, v18, v18 row_bcast:31 row_mask:0xc bank_mask:0xf
	v_add_f32_dpp v20, v20, v20 row_bcast:31 row_mask:0xc bank_mask:0xf
	v_add_f32_dpp v22, v22, v22 row_bcast:31 row_mask:0xc bank_mask:0xf
	v_add_f32_dpp v24, v24, v24 row_bcast:31 row_mask:0xc bank_mask:0xf
	v_add_f32_dpp v26, v26, v26 row_bcast:31 row_mask:0xc bank_mask:0xf
	v_add_f32_dpp v28, v28, v28 row_bcast:31 row_mask:0xc bank_mask:0xf
	v_add_f32_dpp v30, v30, v30 row_bcast:31 row_mask:0xc bank_mask:0xf
	s_nop 0
	v_readlane_b32 s14, v16, 63
	v_readlane_b32 s15, v18, 63
	v_readlane_b32 s16, v20, 63
	v_readlane_b32 s17, v22, 63
	v_readlane_b32 s18, v24, 63
	v_readlane_b32 s19, v26, 63
	v_readlane_b32 s46, v28, 63
	v_readlane_b32 s47, v30, 63
	s_nop 1
	v_writelane_b32 v4, s14, 16
	v_writelane_b32 v4, s15, 17
	v_writelane_b32 v4, s16, 18
	v_writelane_b32 v4, s17, 19
	v_writelane_b32 v4, s18, 20
	v_writelane_b32 v4, s19, 21
	v_writelane_b32 v4, s46, 22
	v_writelane_b32 v4, s47, 23
	s_mov_b32 s62, s8
	s_cmp_lt_i32 s8, 32768
	s_cbranch_scc1 .Lp0r_row3
	s_movk_i32 s6, 24
	s_branch .Lp0r_flush

; #define GAS __attribute__((address_space(1)))
; #define LAS __attribute__((address_space(3)))
; __device__ __forceinline__ unsigned pk2(float lo, float hi) { return pg8::cvt_pk_bf16_c(lo, hi); }
; __device__ __forceinline__ void p0_prologue(const Args& a, LAS unsigned char* lds, int vcu, int G, int tid, int lane, int wave) {
;     ...
;     for (int m = gw; m < T; m += NGW) {
;         f32x4 v[4]; float s2 = 0.f;
; #pragma unroll
;         for (int j = 0; j < 4; ++j) { v[j] = nv[j]; s2 += (v[j].x * v[j].x + v[j].y * v[j].y) + (v[j].z * v[j].z + v[j].w * v[j].w); }
;         if (m + NGW < T) { const GAS f32x4* xr = (const GAS f32x4*)(x + (size_t)(m + NGW) * DM) + lane;
; #pragma unroll
;             for (int j = 0; j < 4; ++j) nv[j] = xr[64 * j]; }
;         const float rstd = 1.0f / sqrtf(wave_sum(s2) * (1.f / DM) + EPS);
; #pragma unroll
;         for (int j = 0; j < 4; ++j) v[j] = v[j] * rstd * gv[j];
;         GAS unsigned long long* o8 = (GAS unsigned long long*)(XN + (size_t)m * DM) + lane;
; #pragma unroll
;         for (int j = 0; j < 4; ++j) o8[64 * j] = (unsigned long long)pk2(v[j].x, v[j].y) | ((unsigned long long)pk2(v[j].z, v[j].w) << 32);
;         float f[8];
; #pragma unroll
;         for (int h = 0; h < 8; ++h) { float acc = 0.f;
; #pragma unroll
;             for (int j = 0; j < 4; ++j) { const f32x4 w = *(const LAS f32x4*)(wf + h * 1024 + 256 * j + 4 * lane); acc += (v[j].x * w.x + v[j].y * w.y) + (v[j].z * w.z + v[j].w * w.w); }
.Lp0r_wd_3:
	s_cmp_lt_i32 s11, 32768
	s_cbranch_scc0 .Lp0r_nl_3
	s_lshl_b32 s0, s11, 12
	s_add_u32 s0, s36, s0
	s_addc_u32 s1, s37, 0
	global_load_dwordx4 v[80:83], v2, s[0:1] offset:0
	global_load_dwordx4 v[84:87], v2, s[0:1] offset:1024
	global_load_dwordx4 v[88:91], v2, s[0:1] offset:2048
	global_load_dwordx4 v[92:95], v2, s[0:1] offset:3072
.Lp0r_nl_3:
	v_pk_mul_f32 v[10:11], v[96:97], v[96:97]
	v_pk_mul_f32 v[12:13], v[98:99], v[98:99]
	v_pk_fma_f32 v[10:11], v[100:101], v[100:101], v[10:11]
	v_pk_fma_f32 v[12:13], v[102:103], v[102:103], v[12:13]
	v_pk_fma_f32 v[10:11], v[104:105], v[104:105], v[10:11]
	v_pk_fma_f32 v[12:13], v[106:107], v[106:107], v[12:13]
	v_pk_fma_f32 v[10:11], v[108:109], v[108:109], v[10:11]
	v_pk_fma_f32 v[12:13], v[110:111], v[110:111], v[12:13]
	s_lshl_b32 s12, s62, 11
	v_pk_add_f32 v[10:11], v[10:11], v[12:13]
	s_add_u32 s12, s26, s12
	s_addc_u32 s13, s27, 0
	v_add_f32_e32 v6, v10, v11
	s_nop 1
	v_add_f32_dpp v6, v6, v6 quad_perm:[1,0,3,2] row_mask:0xf bank_mask:0xf
	s_nop 1
	v_add_f32_dpp v6, v6, v6 quad_perm:[2,3,0,1] row_mask:0xf bank_mask:0xf
	s_nop 1
	v_add_f32_dpp v6, v6, v6 row_half_mirror row_mask:0xf bank_mask:0xf
	s_nop 1
	v_add_f32_dpp v6, v6, v6 row_mirror row_mask:0xf bank_mask:0xf
	s_nop 1
	v_add_f32_dpp v6, v6, v6 row_bcast:15 row_mask:0xa bank_mask:0xf
	s_nop 1
	v_add_f32_dpp v6, v6, v6 row_bcast:31 row_mask:0xc bank_mask:0xf
	v_mov_b32_e32 v7, 0x358637bd
	s_nop 0
	v_fmamk_f32 v6, v6, 0x3a800000, v7
	s_nop 0
	v_rsq_f32_e32 v7, v6
	v_mul_f32_e32 v6, 0.5, v6
	s_nop 0
	v_mul_f32_e32 v6, v6, v7
	s_nop 0
	v_fma_f32 v6, -v6, v7, 0.5
	s_nop 0
	v_fma_f32 v7, v7, v6, v7
	s_nop 1
	v_readlane_b32 s4, v7, 63
	s_nop 3
	v_pk_mul_f32 v[96:97], v[96:97], s[4:5] op_sel_hi:[1,0]
	v_pk_mul_f32 v[98:99], v[98:99], s[4:5] op_sel_hi:[1,0]
	v_pk_mul_f32 v[100:101], v[100:101], s[4:5] op_sel_hi:[1,0]
	v_pk_mul_f32 v[102:103], v[102:103], s[4:5] op_sel_hi:[1,0]
	v_pk_mul_f32 v[104:105], v[104:105], s[4:5] op_sel_hi:[1,0]
	v_pk_mul_f32 v[106:107], v[106:107], s[4:5] op_sel_hi:[1,0]
	v_pk_mul_f32 v[108:109], v[108:109], s[4:5] op_sel_hi:[1,0]
	v_pk_mul_f32 v[110:111], v[110:111], s[4:5] op_sel_hi:[1,0]
	v_pk_mul_f32 v[96:97], v[96:97], v[112:113]
	v_pk_mul_f32 v[98:99], v[98:99], v[114:115]
	v_pk_mul_f32 v[100:101], v[100:101], v[116:117]
	v_pk_mul_f32 v[102:103], v[102:103], v[118:119]
	v_pk_mul_f32 v[104:105], v[104:105], v[120:121]
	v_pk_mul_f32 v[106:107], v[106:107], v[122:123]
	v_pk_mul_f32 v[108:109], v[108:109], v[124:125]
	v_pk_mul_f32 v[110:111], v[110:111], v[126:127]
	v_cvt_pk_bf16_f32 v38, v96, v97
	v_cvt_pk_bf16_f32 v39, v98, v99
	v_cvt_pk_bf16_f32 v40, v100, v101
	v_cvt_pk_bf16_f32 v41, v102, v103
	v_cvt_pk_bf16_f32 v42, v104, v105
	v_cvt_pk_bf16_f32 v43, v106, v107
	v_cvt_pk_bf16_f32 v44, v108, v109
	v_cvt_pk_bf16_f32 v45, v110, v111
	global_store_dwordx2 v3, v[38:39], s[12:13] offset:0
	global_store_dwordx2 v3, v[40:41], s[12:13] offset:512
	global_store_dwordx2 v3, v[42:43], s[12:13] offset:1024
	global_store_dwordx2 v3, v[44:45], s[12:13] offset:1536
	v_pk_mul_f32 v[16:17], v[96:97], v[128:129]
	v_pk_mul_f32 v[18:19], v[96:97], v[144:145]
	v_pk_mul_f32 v[20:21], v[96:97], v[160:161]
	v_pk_mul_f32 v[22:23], v[96:97], v[176:177]
	v_pk_mul_f32 v[24:25], v[96:97], v[192:193]
	v_pk_mul_f32 v[26:27], v[96:97], v[208:209]
	v_pk_mul_f32 v[28:29], v[96:97], v[224:225]
	v_pk_mul_f32 v[30:31], v[96:97], v[240:241]
	v_pk_fma_f32 v[16:17], v[98:99], v[130:131], v[16:17]
	v_pk_fma_f32 v[18:19], v[98:99], v[146:147], v[18:19]
	v_pk_fma_f32 v[20:21], v[98:99], v[162:163], v[20:21]
	v_pk_fma_f32 v[22:23], v[98:99], v[178:179], v[22:23]
	v_pk_fma_f32 v[24:25], v[98:99], v[194:195], v[24:25]
	v_pk_fma_f32 v[26:27], v[98:99], v[210:211], v[26:27]
	v_pk_fma_f32 v[28:29], v[98:99], v[226:227], v[28:29]
	v_pk_fma_f32 v[30:31], v[98:99], v[242:243], v[30:31]
	v_pk_fma_f32 v[16:17], v[100:101], v[132:133], v[16:17]
	v_pk_fma_f32 v[18:19], v[100:101], v[148:149], v[18:19]
	v_pk_fma_f32 v[20:21], v[100:101], v[164:165], v[20:21]
	v_pk_fma_f32 v[22:23], v[100:101], v[180:181], v[22:23]
	v_pk_fma_f32 v[24:25], v[100:101], v[196:197], v[24:25]
	v_pk_fma_f32 v[26:27], v[100:101], v[212:213], v[26:27]
	v_pk_fma_f32 v[28:29], v[100:101], v[228:229], v[28:29]
	v_pk_fma_f32 v[30:31], v[100:101], v[244:245], v[30:31]
	v_pk_fma_f32 v[16:17], v[102:103], v[134:135], v[16:17]
	v_pk_fma_f32 v[18:19], v[102:103], v[150:151], v[18:19]
	v_pk_fma_f32 v[20:21], v[102:103], v[166:167], v[20:21]
	v_pk_fma_f32 v[22:23], v[102:103], v[182:183], v[22:23]
	v_pk_fma_f32 v[24:25], v[102:103], v[198:199], v[24:25]
	v_pk_fma_f32 v[26:27], v[102:103], v[214:215], v[26:27]
	v_pk_fma_f32 v[28:29], v[102:103], v[230:231], v[28:29]
	v_pk_fma_f32 v[30:31], v[102:103], v[246:247], v[30:31]
	v_pk_fma_f32 v[16:17], v[104:105], v[136:137], v[16:17]
	v_pk_fma_f32 v[18:19], v[104:105], v[152:153], v[18:19]
	v_pk_fma_f32 v[20:21], v[104:105], v[168:169], v[20:21]
	v_pk_fma_f32 v[22:23], v[104:105], v[184:185], v[22:23]
	v_pk_fma_f32 v[24:25], v[104:105], v[200:201], v[24:25]
	v_pk_fma_f32 v[26:27], v[104:105], v[216:217], v[26:27]
	v_pk_fma_f32 v[28:29], v[104:105], v[232:233], v[28:29]
	v_pk_fma_f32 v[30:31], v[104:105], v[248:249], v[30:31]
	v_pk_fma_f32 v[16:17], v[106:107], v[138:139], v[16:17]
	v_pk_fma_f32 v[18:19], v[106:107], v[154:155], v[18:19]
	v_pk_fma_f32 v[20:21], v[106:107], v[170:171], v[20:21]
	v_pk_fma_f32 v[22:23], v[106:107], v[186:187], v[22:23]
; #define LAS __attribute__((address_space(3)))
; __device__ __forceinline__ void p0_prologue(const Args& a, LAS unsigned char* lds, int vcu, int G, int tid, int lane, int wave) {
;     ...
;         for (int h = 0; h < 8; ++h) { float acc = 0.f;
; #pragma unroll
;             for (int j = 0; j < 4; ++j) { const f32x4 w = *(const LAS f32x4*)(wf + h * 1024 + 256 * j + 4 * lane); acc += (v[j].x * w.x + v[j].y * w.y) + (v[j].z * w.z + v[j].w * w.w); }
;             f[h] = wave_sum(acc); }
;         float fz = f[0];
; #pragma unroll
;         for (int h = 1; h < 8; ++h) fz = (lane == h) ? f[h] : fz;
	v_pk_fma_f32 v[24:25], v[106:107], v[202:203], v[24:25]
	v_pk_fma_f32 v[26:27], v[106:107], v[218:219], v[26:27]
	v_pk_fma_f32 v[28:29], v[106:107], v[234:235], v[28:29]
	v_pk_fma_f32 v[30:31], v[106:107], v[250:251], v[30:31]
	v_pk_fma_f32 v[16:17], v[108:109], v[140:141], v[16:17]
	v_pk_fma_f32 v[18:19], v[108:109], v[156:157], v[18:19]
	v_pk_fma_f32 v[20:21], v[108:109], v[172:173], v[20:21]
	v_pk_fma_f32 v[22:23], v[108:109], v[188:189], v[22:23]
	v_pk_fma_f32 v[24:25], v[108:109], v[204:205], v[24:25]
	v_pk_fma_f32 v[26:27], v[108:109], v[220:221], v[26:27]
	v_pk_fma_f32 v[28:29], v[108:109], v[236:237], v[28:29]
	v_pk_fma_f32 v[30:31], v[108:109], v[252:253], v[30:31]
	v_pk_fma_f32 v[16:17], v[110:111], v[142:143], v[16:17]
	v_pk_fma_f32 v[18:19], v[110:111], v[158:159], v[18:19]
	v_pk_fma_f32 v[20:21], v[110:111], v[174:175], v[20:21]
	v_pk_fma_f32 v[22:23], v[110:111], v[190:191], v[22:23]
	v_pk_fma_f32 v[24:25], v[110:111], v[206:207], v[24:25]
	v_pk_fma_f32 v[26:27], v[110:111], v[222:223], v[26:27]
	v_pk_fma_f32 v[28:29], v[110:111], v[238:239], v[28:29]
	v_pk_fma_f32 v[30:31], v[110:111], v[254:255], v[30:31]
	v_add_f32_e32 v16, v16, v17
	v_add_f32_e32 v18, v18, v19
	v_add_f32_e32 v20, v20, v21
	v_add_f32_e32 v22, v22, v23
	v_add_f32_e32 v24, v24, v25
	v_add_f32_e32 v26, v26, v27
	v_add_f32_e32 v28, v28, v29
	v_add_f32_e32 v30, v30, v31
	v_add_f32_dpp v16, v16, v16 quad_perm:[1,0,3,2] row_mask:0xf bank_mask:0xf
	v_add_f32_dpp v18, v18, v18 quad_perm:[1,0,3,2] row_mask:0xf bank_mask:0xf
	v_add_f32_dpp v20, v20, v20 quad_perm:[1,0,3,2] row_mask:0xf bank_mask:0xf
	v_add_f32_dpp v22, v22, v22 quad_perm:[1,0,3,2] row_mask:0xf bank_mask:0xf
	v_add_f32_dpp v24, v24, v24 quad_perm:[1,0,3,2] row_mask:0xf bank_mask:0xf
	v_add_f32_dpp v26, v26, v26 quad_perm:[1,0,3,2] row_mask:0xf bank_mask:0xf
	v_add_f32_dpp v28, v28, v28 quad_perm:[1,0,3,2] row_mask:0xf bank_mask:0xf
	v_add_f32_dpp v30, v30, v30 quad_perm:[1,0,3,2] row_mask:0xf bank_mask:0xf
	v_add_f32_dpp v16, v16, v16 quad_perm:[2,3,0,1] row_mask:0xf bank_mask:0xf
	v_add_f32_dpp v18, v18, v18 quad_perm:[2,3,0,1] row_mask:0xf bank_mask:0xf
	v_add_f32_dpp v20, v20, v20 quad_perm:[2,3,0,1] row_mask:0xf bank_mask:0xf
	v_add_f32_dpp v22, v22, v22 quad_perm:[2,3,0,1] row_mask:0xf bank_mask:0xf
	v_add_f32_dpp v24, v24, v24 quad_perm:[2,3,0,1] row_mask:0xf bank_mask:0xf
	v_add_f32_dpp v26, v26, v26 quad_perm:[2,3,0,1] row_mask:0xf bank_mask:0xf
	v_add_f32_dpp v28, v28, v28 quad_perm:[2,3,0,1] row_mask:0xf bank_mask:0xf
	v_add_f32_dpp v30, v30, v30 quad_perm:[2,3,0,1] row_mask:0xf bank_mask:0xf
	v_add_f32_dpp v16, v16, v16 row_half_mirror row_mask:0xf bank_mask:0xf
	v_add_f32_dpp v18, v18, v18 row_half_mirror row_mask:0xf bank_mask:0xf
	v_add_f32_dpp v20, v20, v20 row_half_mirror row_mask:0xf bank_mask:0xf
	v_add_f32_dpp v22, v22, v22 row_half_mirror row_mask:0xf bank_mask:0xf
	v_add_f32_dpp v24, v24, v24 row_half_mirror row_mask:0xf bank_mask:0xf
	v_add_f32_dpp v26, v26, v26 row_half_mirror row_mask:0xf bank_mask:0xf
	v_add_f32_dpp v28, v28, v28 row_half_mirror row_mask:0xf bank_mask:0xf
	v_add_f32_dpp v30, v30, v30 row_half_mirror row_mask:0xf bank_mask:0xf
	v_add_f32_dpp v16, v16, v16 row_mirror row_mask:0xf bank_mask:0xf
	v_add_f32_dpp v18, v18, v18 row_mirror row_mask:0xf bank_mask:0xf
	v_add_f32_dpp v20, v20, v20 row_mirror row_mask:0xf bank_mask:0xf
	v_add_f32_dpp v22, v22, v22 row_mirror row_mask:0xf bank_mask:0xf
	v_add_f32_dpp v24, v24, v24 row_mirror row_mask:0xf bank_mask:0xf
	v_add_f32_dpp v26, v26, v26 row_mirror row_mask:0xf bank_mask:0xf
	v_add_f32_dpp v28, v28, v28 row_mirror row_mask:0xf bank_mask:0xf
	v_add_f32_dpp v30, v30, v30 row_mirror row_mask:0xf bank_mask:0xf
	v_add_f32_dpp v16, v16, v16 row_bcast:15 row_mask:0xa bank_mask:0xf
	v_add_f32_dpp v18, v18, v18 row_bcast:15 row_mask:0xa bank_mask:0xf
	v_add_f32_dpp v20, v20, v20 row_bcast:15 row_mask:0xa bank_mask:0xf
	v_add_f32_dpp v22, v22, v22 row_bcast:15 row_mask:0xa bank_mask:0xf
	v_add_f32_dpp v24, v24, v24 row_bcast:15 row_mask:0xa bank_mask:0xf
	v_add_f32_dpp v26, v26, v26 row_bcast:15 row_mask:0xa bank_mask:0xf
	v_add_f32_dpp v28, v28, v28 row_bcast:15 row_mask:0xa bank_mask:0xf
	v_add_f32_dpp v30, v30, v30 row_bcast:15 row_mask:0xa bank_mask:0xf
	v_add_f32_dpp v16, v16, v16 row_bcast:31 row_mask:0xc bank_mask:0xf
	v_add_f32_dpp v18, v18, v18 row_bcast:31 row_mask:0xc bank_mask:0xf
	v_add_f32_dpp v20, v20, v20 row_bcast:31 row_mask:0xc bank_mask:0xf
	v_add_f32_dpp v22, v22, v22 row_bcast:31 row_mask:0xc bank_mask:0xf
	v_add_f32_dpp v24, v24, v24 row_bcast:31 row_mask:0xc bank_mask:0xf
	v_add_f32_dpp v26, v26, v26 row_bcast:31 row_mask:0xc bank_mask:0xf
	v_add_f32_dpp v28, v28, v28 row_bcast:31 row_mask:0xc bank_mask:0xf
	v_add_f32_dpp v30, v30, v30 row_bcast:31 row_mask:0xc bank_mask:0xf
	s_nop 0
	v_readlane_b32 s14, v16, 63
	v_readlane_b32 s15, v18, 63
	v_readlane_b32 s16, v20, 63
	v_readlane_b32 s17, v22, 63
	v_readlane_b32 s18, v24, 63
	v_readlane_b32 s19, v26, 63
	v_readlane_b32 s46, v28, 63
	v_readlane_b32 s47, v30, 63
	s_nop 1
	v_writelane_b32 v4, s14, 24
	v_writelane_b32 v4, s15, 25
	v_writelane_b32 v4, s16, 26
	v_writelane_b32 v4, s17, 27
	v_writelane_b32 v4, s18, 28
	v_writelane_b32 v4, s19, 29
	v_writelane_b32 v4, s46, 30
	v_writelane_b32 v4, s47, 31
	s_mov_b32 s62, s8
	s_cmp_lt_i32 s8, 32768
	s_cbranch_scc1 .Lp0r_row4
	s_movk_i32 s6, 32
	s_branch .Lp0r_flush

; #define GAS __attribute__((address_space(1)))
; #define LAS __attribute__((address_space(3)))
; __device__ __forceinline__ unsigned pk2(float lo, float hi) { return pg8::cvt_pk_bf16_c(lo, hi); }
; __device__ __forceinline__ void p0_prologue(const Args& a, LAS unsigned char* lds, int vcu, int G, int tid, int lane, int wave) {
;     ...
;     for (int m = gw; m < T; m += NGW) {
;         f32x4 v[4]; float s2 = 0.f;
; #pragma unroll
;         for (int j = 0; j < 4; ++j) { v[j] = nv[j]; s2 += (v[j].x * v[j].x + v[j].y * v[j].y) + (v[j].z * v[j].z + v[j].w * v[j].w); }
;         if (m + NGW < T) { const GAS f32x4* xr = (const GAS f32x4*)(x + (size_t)(m + NGW) * DM) + lane;
; #pragma unroll
;             for (int j = 0; j < 4; ++j) nv[j] = xr[64 * j]; }
;         const float rstd = 1.0f / sqrtf(wave_sum(s2) * (1.f / DM) + EPS);
; #pragma unroll
;         for (int j = 0; j < 4; ++j) v[j] = v[j] * rstd * gv[j];
;         GAS unsigned long long* o8 = (GAS unsigned long long*)(XN + (size_t)m * DM) + lane;
; #pragma unroll
;         for (int j = 0; j < 4; ++j) o8[64 * j] = (unsigned long long)pk2(v[j].x, v[j].y) | ((unsigned long long)pk2(v[j].z, v[j].w) << 32);
;         float f[8];
; #pragma unroll
;         for (int h = 0; h < 8; ++h) { float acc = 0.f;
; #pragma unroll
;             for (int j = 0; j < 4; ++j) { const f32x4 w = *(const LAS f32x4*)(wf + h * 1024 + 256 * j + 4 * lane); acc += (v[j].x * w.x + v[j].y * w.y) + (v[j].z * w.z + v[j].w * w.w); }
.Lp0r_nl_4:
	v_pk_mul_f32 v[10:11], v[48:49], v[48:49]
	v_pk_mul_f32 v[12:13], v[50:51], v[50:51]
	v_pk_fma_f32 v[10:11], v[52:53], v[52:53], v[10:11]
	v_pk_fma_f32 v[12:13], v[54:55], v[54:55], v[12:13]
	v_pk_fma_f32 v[10:11], v[56:57], v[56:57], v[10:11]
	v_pk_fma_f32 v[12:13], v[58:59], v[58:59], v[12:13]
	v_pk_fma_f32 v[10:11], v[60:61], v[60:61], v[10:11]
	v_pk_fma_f32 v[12:13], v[62:63], v[62:63], v[12:13]
	s_lshl_b32 s12, s62, 11
	v_pk_add_f32 v[10:11], v[10:11], v[12:13]
	s_add_u32 s12, s26, s12
	s_addc_u32 s13, s27, 0
	v_add_f32_e32 v6, v10, v11
	s_nop 1
	v_add_f32_dpp v6, v6, v6 quad_perm:[1,0,3,2] row_mask:0xf bank_mask:0xf
	s_nop 1
	v_add_f32_dpp v6, v6, v6 quad_perm:[2,3,0,1] row_mask:0xf bank_mask:0xf
	s_nop 1
	v_add_f32_dpp v6, v6, v6 row_half_mirror row_mask:0xf bank_mask:0xf
	s_nop 1
	v_add_f32_dpp v6, v6, v6 row_mirror row_mask:0xf bank_mask:0xf
	s_nop 1
	v_add_f32_dpp v6, v6, v6 row_bcast:15 row_mask:0xa bank_mask:0xf
	s_nop 1
	v_add_f32_dpp v6, v6, v6 row_bcast:31 row_mask:0xc bank_mask:0xf
	v_mov_b32_e32 v7, 0x358637bd
	s_nop 0
	v_fmamk_f32 v6, v6, 0x3a800000, v7
	s_nop 0
	v_rsq_f32_e32 v7, v6
	v_mul_f32_e32 v6, 0.5, v6
	s_nop 0
	v_mul_f32_e32 v6, v6, v7
	s_nop 0
	v_fma_f32 v6, -v6, v7, 0.5
	s_nop 0
	v_fma_f32 v7, v7, v6, v7
	s_nop 1
	v_readlane_b32 s4, v7, 63
	s_nop 3
	v_pk_mul_f32 v[48:49], v[48:49], s[4:5] op_sel_hi:[1,0]
	v_pk_mul_f32 v[50:51], v[50:51], s[4:5] op_sel_hi:[1,0]
	v_pk_mul_f32 v[52:53], v[52:53], s[4:5] op_sel_hi:[1,0]
	v_pk_mul_f32 v[54:55], v[54:55], s[4:5] op_sel_hi:[1,0]
	v_pk_mul_f32 v[56:57], v[56:57], s[4:5] op_sel_hi:[1,0]
	v_pk_mul_f32 v[58:59], v[58:59], s[4:5] op_sel_hi:[1,0]
	v_pk_mul_f32 v[60:61], v[60:61], s[4:5] op_sel_hi:[1,0]
	v_pk_mul_f32 v[62:63], v[62:63], s[4:5] op_sel_hi:[1,0]
	v_pk_mul_f32 v[48:49], v[48:49], v[112:113]
	v_pk_mul_f32 v[50:51], v[50:51], v[114:115]
	v_pk_mul_f32 v[52:53], v[52:53], v[116:117]
	v_pk_mul_f32 v[54:55], v[54:55], v[118:119]
	v_pk_mul_f32 v[56:57], v[56:57], v[120:121]
	v_pk_mul_f32 v[58:59], v[58:59], v[122:123]
	v_pk_mul_f32 v[60:61], v[60:61], v[124:125]
	v_pk_mul_f32 v[62:63], v[62:63], v[126:127]
	v_cvt_pk_bf16_f32 v38, v48, v49
	v_cvt_pk_bf16_f32 v39, v50, v51
	v_cvt_pk_bf16_f32 v40, v52, v53
	v_cvt_pk_bf16_f32 v41, v54, v55
	v_cvt_pk_bf16_f32 v42, v56, v57
	v_cvt_pk_bf16_f32 v43, v58, v59
	v_cvt_pk_bf16_f32 v44, v60, v61
	v_cvt_pk_bf16_f32 v45, v62, v63
	global_store_dwordx2 v3, v[38:39], s[12:13] offset:0
	global_store_dwordx2 v3, v[40:41], s[12:13] offset:512
	global_store_dwordx2 v3, v[42:43], s[12:13] offset:1024
	global_store_dwordx2 v3, v[44:45], s[12:13] offset:1536
	v_pk_mul_f32 v[16:17], v[48:49], v[128:129]
	v_pk_mul_f32 v[18:19], v[48:49], v[144:145]
	v_pk_mul_f32 v[20:21], v[48:49], v[160:161]
	v_pk_mul_f32 v[22:23], v[48:49], v[176:177]
	v_pk_mul_f32 v[24:25], v[48:49], v[192:193]
	v_pk_mul_f32 v[26:27], v[48:49], v[208:209]
	v_pk_mul_f32 v[28:29], v[48:49], v[224:225]
	v_pk_mul_f32 v[30:31], v[48:49], v[240:241]
	v_pk_fma_f32 v[16:17], v[50:51], v[130:131], v[16:17]
	v_pk_fma_f32 v[18:19], v[50:51], v[146:147], v[18:19]
	v_pk_fma_f32 v[20:21], v[50:51], v[162:163], v[20:21]
	v_pk_fma_f32 v[22:23], v[50:51], v[178:179], v[22:23]
	v_pk_fma_f32 v[24:25], v[50:51], v[194:195], v[24:25]
	v_pk_fma_f32 v[26:27], v[50:51], v[210:211], v[26:27]
	v_pk_fma_f32 v[28:29], v[50:51], v[226:227], v[28:29]
	v_pk_fma_f32 v[30:31], v[50:51], v[242:243], v[30:31]
	v_pk_fma_f32 v[16:17], v[52:53], v[132:133], v[16:17]
	v_pk_fma_f32 v[18:19], v[52:53], v[148:149], v[18:19]
	v_pk_fma_f32 v[20:21], v[52:53], v[164:165], v[20:21]
	v_pk_fma_f32 v[22:23], v[52:53], v[180:181], v[22:23]
	v_pk_fma_f32 v[24:25], v[52:53], v[196:197], v[24:25]
	v_pk_fma_f32 v[26:27], v[52:53], v[212:213], v[26:27]
	v_pk_fma_f32 v[28:29], v[52:53], v[228:229], v[28:29]
	v_pk_fma_f32 v[30:31], v[52:53], v[244:245], v[30:31]
	v_pk_fma_f32 v[16:17], v[54:55], v[134:135], v[16:17]
	v_pk_fma_f32 v[18:19], v[54:55], v[150:151], v[18:19]
	v_pk_fma_f32 v[20:21], v[54:55], v[166:167], v[20:21]
	v_pk_fma_f32 v[22:23], v[54:55], v[182:183], v[22:23]
	v_pk_fma_f32 v[24:25], v[54:55], v[198:199], v[24:25]
	v_pk_fma_f32 v[26:27], v[54:55], v[214:215], v[26:27]
	v_pk_fma_f32 v[28:29], v[54:55], v[230:231], v[28:29]
	v_pk_fma_f32 v[30:31], v[54:55], v[246:247], v[30:31]
	v_pk_fma_f32 v[16:17], v[56:57], v[136:137], v[16:17]
	v_pk_fma_f32 v[18:19], v[56:57], v[152:153], v[18:19]
	v_pk_fma_f32 v[20:21], v[56:57], v[168:169], v[20:21]
	v_pk_fma_f32 v[22:23], v[56:57], v[184:185], v[22:23]
	v_pk_fma_f32 v[24:25], v[56:57], v[200:201], v[24:25]
	v_pk_fma_f32 v[26:27], v[56:57], v[216:217], v[26:27]
	v_pk_fma_f32 v[28:29], v[56:57], v[232:233], v[28:29]
	v_pk_fma_f32 v[30:31], v[56:57], v[248:249], v[30:31]
	v_pk_fma_f32 v[16:17], v[58:59], v[138:139], v[16:17]
	v_pk_fma_f32 v[18:19], v[58:59], v[154:155], v[18:19]
	v_pk_fma_f32 v[20:21], v[58:59], v[170:171], v[20:21]
	v_pk_fma_f32 v[22:23], v[58:59], v[186:187], v[22:23]
	v_pk_fma_f32 v[24:25], v[58:59], v[202:203], v[24:25]
	v_pk_fma_f32 v[26:27], v[58:59], v[218:219], v[26:27]
	v_pk_fma_f32 v[28:29], v[58:59], v[234:235], v[28:29]
	v_pk_fma_f32 v[30:31], v[58:59], v[250:251], v[30:31]
; #define LAS __attribute__((address_space(3)))
; __device__ __forceinline__ void p0_prologue(const Args& a, LAS unsigned char* lds, int vcu, int G, int tid, int lane, int wave) {
;     ...
;         for (int h = 0; h < 8; ++h) { float acc = 0.f;
; #pragma unroll
;             for (int j = 0; j < 4; ++j) { const f32x4 w = *(const LAS f32x4*)(wf + h * 1024 + 256 * j + 4 * lane); acc += (v[j].x * w.x + v[j].y * w.y) + (v[j].z * w.z + v[j].w * w.w); }
;             f[h] = wave_sum(acc); }
;         float fz = f[0];
; #pragma unroll
;         for (int h = 1; h < 8; ++h) fz = (lane == h) ? f[h] : fz;
	v_pk_fma_f32 v[16:17], v[60:61], v[140:141], v[16:17]
	v_pk_fma_f32 v[18:19], v[60:61], v[156:157], v[18:19]
	v_pk_fma_f32 v[20:21], v[60:61], v[172:173], v[20:21]
	v_pk_fma_f32 v[22:23], v[60:61], v[188:189], v[22:23]
	v_pk_fma_f32 v[24:25], v[60:61], v[204:205], v[24:25]
	v_pk_fma_f32 v[26:27], v[60:61], v[220:221], v[26:27]
	v_pk_fma_f32 v[28:29], v[60:61], v[236:237], v[28:29]
	v_pk_fma_f32 v[30:31], v[60:61], v[252:253], v[30:31]
	v_pk_fma_f32 v[16:17], v[62:63], v[142:143], v[16:17]
	v_pk_fma_f32 v[18:19], v[62:63], v[158:159], v[18:19]
	v_pk_fma_f32 v[20:21], v[62:63], v[174:175], v[20:21]
	v_pk_fma_f32 v[22:23], v[62:63], v[190:191], v[22:23]
	v_pk_fma_f32 v[24:25], v[62:63], v[206:207], v[24:25]
	v_pk_fma_f32 v[26:27], v[62:63], v[222:223], v[26:27]
	v_pk_fma_f32 v[28:29], v[62:63], v[238:239], v[28:29]
	v_pk_fma_f32 v[30:31], v[62:63], v[254:255], v[30:31]
	v_add_f32_e32 v16, v16, v17
	v_add_f32_e32 v18, v18, v19
	v_add_f32_e32 v20, v20, v21
	v_add_f32_e32 v22, v22, v23
	v_add_f32_e32 v24, v24, v25
	v_add_f32_e32 v26, v26, v27
	v_add_f32_e32 v28, v28, v29
	v_add_f32_e32 v30, v30, v31
	v_add_f32_dpp v16, v16, v16 quad_perm:[1,0,3,2] row_mask:0xf bank_mask:0xf
	v_add_f32_dpp v18, v18, v18 quad_perm:[1,0,3,2] row_mask:0xf bank_mask:0xf
	v_add_f32_dpp v20, v20, v20 quad_perm:[1,0,3,2] row_mask:0xf bank_mask:0xf
	v_add_f32_dpp v22, v22, v22 quad_perm:[1,0,3,2] row_mask:0xf bank_mask:0xf
	v_add_f32_dpp v24, v24, v24 quad_perm:[1,0,3,2] row_mask:0xf bank_mask:0xf
	v_add_f32_dpp v26, v26, v26 quad_perm:[1,0,3,2] row_mask:0xf bank_mask:0xf
	v_add_f32_dpp v28, v28, v28 quad_perm:[1,0,3,2] row_mask:0xf bank_mask:0xf
	v_add_f32_dpp v30, v30, v30 quad_perm:[1,0,3,2] row_mask:0xf bank_mask:0xf
	v_add_f32_dpp v16, v16, v16 quad_perm:[2,3,0,1] row_mask:0xf bank_mask:0xf
	v_add_f32_dpp v18, v18, v18 quad_perm:[2,3,0,1] row_mask:0xf bank_mask:0xf
	v_add_f32_dpp v20, v20, v20 quad_perm:[2,3,0,1] row_mask:0xf bank_mask:0xf
	v_add_f32_dpp v22, v22, v22 quad_perm:[2,3,0,1] row_mask:0xf bank_mask:0xf
	v_add_f32_dpp v24, v24, v24 quad_perm:[2,3,0,1] row_mask:0xf bank_mask:0xf
	v_add_f32_dpp v26, v26, v26 quad_perm:[2,3,0,1] row_mask:0xf bank_mask:0xf
	v_add_f32_dpp v28, v28, v28 quad_perm:[2,3,0,1] row_mask:0xf bank_mask:0xf
	v_add_f32_dpp v30, v30, v30 quad_perm:[2,3,0,1] row_mask:0xf bank_mask:0xf
	v_add_f32_dpp v16, v16, v16 row_half_mirror row_mask:0xf bank_mask:0xf
	v_add_f32_dpp v18, v18, v18 row_half_mirror row_mask:0xf bank_mask:0xf
	v_add_f32_dpp v20, v20, v20 row_half_mirror row_mask:0xf bank_mask:0xf
	v_add_f32_dpp v22, v22, v22 row_half_mirror row_mask:0xf bank_mask:0xf
	v_add_f32_dpp v24, v24, v24 row_half_mirror row_mask:0xf bank_mask:0xf
	v_add_f32_dpp v26, v26, v26 row_half_mirror row_mask:0xf bank_mask:0xf
	v_add_f32_dpp v28, v28, v28 row_half_mirror row_mask:0xf bank_mask:0xf
	v_add_f32_dpp v30, v30, v30 row_half_mirror row_mask:0xf bank_mask:0xf
	v_add_f32_dpp v16, v16, v16 row_mirror row_mask:0xf bank_mask:0xf
	v_add_f32_dpp v18, v18, v18 row_mirror row_mask:0xf bank_mask:0xf
	v_add_f32_dpp v20, v20, v20 row_mirror row_mask:0xf bank_mask:0xf
	v_add_f32_dpp v22, v22, v22 row_mirror row_mask:0xf bank_mask:0xf
	v_add_f32_dpp v24, v24, v24 row_mirror row_mask:0xf bank_mask:0xf
	v_add_f32_dpp v26, v26, v26 row_mirror row_mask:0xf bank_mask:0xf
	v_add_f32_dpp v28, v28, v28 row_mirror row_mask:0xf bank_mask:0xf
	v_add_f32_dpp v30, v30, v30 row_mirror row_mask:0xf bank_mask:0xf
	v_add_f32_dpp v16, v16, v16 row_bcast:15 row_mask:0xa bank_mask:0xf
	v_add_f32_dpp v18, v18, v18 row_bcast:15 row_mask:0xa bank_mask:0xf
	v_add_f32_dpp v20, v20, v20 row_bcast:15 row_mask:0xa bank_mask:0xf
	v_add_f32_dpp v22, v22, v22 row_bcast:15 row_mask:0xa bank_mask:0xf
	v_add_f32_dpp v24, v24, v24 row_bcast:15 row_mask:0xa bank_mask:0xf
	v_add_f32_dpp v26, v26, v26 row_bcast:15 row_mask:0xa bank_mask:0xf
	v_add_f32_dpp v28, v28, v28 row_bcast:15 row_mask:0xa bank_mask:0xf
	v_add_f32_dpp v30, v30, v30 row_bcast:15 row_mask:0xa bank_mask:0xf
	v_add_f32_dpp v16, v16, v16 row_bcast:31 row_mask:0xc bank_mask:0xf
	v_add_f32_dpp v18, v18, v18 row_bcast:31 row_mask:0xc bank_mask:0xf
	v_add_f32_dpp v20, v20, v20 row_bcast:31 row_mask:0xc bank_mask:0xf
	v_add_f32_dpp v22, v22, v22 row_bcast:31 row_mask:0xc bank_mask:0xf
	v_add_f32_dpp v24, v24, v24 row_bcast:31 row_mask:0xc bank_mask:0xf
	v_add_f32_dpp v26, v26, v26 row_bcast:31 row_mask:0xc bank_mask:0xf
	v_add_f32_dpp v28, v28, v28 row_bcast:31 row_mask:0xc bank_mask:0xf
	v_add_f32_dpp v30, v30, v30 row_bcast:31 row_mask:0xc bank_mask:0xf
	s_nop 0
	v_readlane_b32 s14, v16, 63
	v_readlane_b32 s15, v18, 63
	v_readlane_b32 s16, v20, 63
	v_readlane_b32 s17, v22, 63
	v_readlane_b32 s18, v24, 63
	v_readlane_b32 s19, v26, 63
	v_readlane_b32 s46, v28, 63
	v_readlane_b32 s47, v30, 63
	s_nop 1
	v_writelane_b32 v4, s14, 32
	v_writelane_b32 v4, s15, 33
	v_writelane_b32 v4, s16, 34
	v_writelane_b32 v4, s17, 35
	v_writelane_b32 v4, s18, 36
	v_writelane_b32 v4, s19, 37
	v_writelane_b32 v4, s46, 38
	v_writelane_b32 v4, s47, 39
	s_mov_b32 s62, s8
	s_cmp_lt_i32 s8, 32768
	s_cbranch_scc1 .Lp0r_row5
	s_movk_i32 s6, 40
	s_branch .Lp0r_flush

; #define GAS __attribute__((address_space(1)))
; #define LAS __attribute__((address_space(3)))
; __device__ __forceinline__ unsigned pk2(float lo, float hi) { return pg8::cvt_pk_bf16_c(lo, hi); }
; __device__ __forceinline__ void p0_prologue(const Args& a, LAS unsigned char* lds, int vcu, int G, int tid, int lane, int wave) {
;     ...
;     for (int m = gw; m < T; m += NGW) {
;         f32x4 v[4]; float s2 = 0.f;
; #pragma unroll
;         for (int j = 0; j < 4; ++j) { v[j] = nv[j]; s2 += (v[j].x * v[j].x + v[j].y * v[j].y) + (v[j].z * v[j].z + v[j].w * v[j].w); }
;         if (m + NGW < T) { const GAS f32x4* xr = (const GAS f32x4*)(x + (size_t)(m + NGW) * DM) + lane;
; #pragma unroll
;             for (int j = 0; j < 4; ++j) nv[j] = xr[64 * j]; }
;         const float rstd = 1.0f / sqrtf(wave_sum(s2) * (1.f / DM) + EPS);
; #pragma unroll
;         for (int j = 0; j < 4; ++j) v[j] = v[j] * rstd * gv[j];
;         GAS unsigned long long* o8 = (GAS unsigned long long*)(XN + (size_t)m * DM) + lane;
; #pragma unroll
;         for (int j = 0; j < 4; ++j) o8[64 * j] = (unsigned long long)pk2(v[j].x, v[j].y) | ((unsigned long long)pk2(v[j].z, v[j].w) << 32);
;         float f[8];
; #pragma unroll
;         for (int h = 0; h < 8; ++h) { float acc = 0.f;
; #pragma unroll
;             for (int j = 0; j < 4; ++j) { const f32x4 w = *(const LAS f32x4*)(wf + h * 1024 + 256 * j + 4 * lane); acc += (v[j].x * w.x + v[j].y * w.y) + (v[j].z * w.z + v[j].w * w.w); }
.Lp0r_nl_5:
	v_pk_mul_f32 v[10:11], v[64:65], v[64:65]
	v_pk_mul_f32 v[12:13], v[66:67], v[66:67]
	v_pk_fma_f32 v[10:11], v[68:69], v[68:69], v[10:11]
	v_pk_fma_f32 v[12:13], v[70:71], v[70:71], v[12:13]
	v_pk_fma_f32 v[10:11], v[72:73], v[72:73], v[10:11]
	v_pk_fma_f32 v[12:13], v[74:75], v[74:75], v[12:13]
	v_pk_fma_f32 v[10:11], v[76:77], v[76:77], v[10:11]
	v_pk_fma_f32 v[12:13], v[78:79], v[78:79], v[12:13]
	s_lshl_b32 s12, s62, 11
	v_pk_add_f32 v[10:11], v[10:11], v[12:13]
	s_add_u32 s12, s26, s12
	s_addc_u32 s13, s27, 0
	v_add_f32_e32 v6, v10, v11
	s_nop 1
	v_add_f32_dpp v6, v6, v6 quad_perm:[1,0,3,2] row_mask:0xf bank_mask:0xf
	s_nop 1
	v_add_f32_dpp v6, v6, v6 quad_perm:[2,3,0,1] row_mask:0xf bank_mask:0xf
	s_nop 1
	v_add_f32_dpp v6, v6, v6 row_half_mirror row_mask:0xf bank_mask:0xf
	s_nop 1
	v_add_f32_dpp v6, v6, v6 row_mirror row_mask:0xf bank_mask:0xf
	s_nop 1
	v_add_f32_dpp v6, v6, v6 row_bcast:15 row_mask:0xa bank_mask:0xf
	s_nop 1
	v_add_f32_dpp v6, v6, v6 row_bcast:31 row_mask:0xc bank_mask:0xf
	v_mov_b32_e32 v7, 0x358637bd
	s_nop 0
	v_fmamk_f32 v6, v6, 0x3a800000, v7
	s_nop 0
	v_rsq_f32_e32 v7, v6
	v_mul_f32_e32 v6, 0.5, v6
	s_nop 0
	v_mul_f32_e32 v6, v6, v7
	s_nop 0
	v_fma_f32 v6, -v6, v7, 0.5
	s_nop 0
	v_fma_f32 v7, v7, v6, v7
	s_nop 1
	v_readlane_b32 s4, v7, 63
	s_nop 3
	v_pk_mul_f32 v[64:65], v[64:65], s[4:5] op_sel_hi:[1,0]
	v_pk_mul_f32 v[66:67], v[66:67], s[4:5] op_sel_hi:[1,0]
	v_pk_mul_f32 v[68:69], v[68:69], s[4:5] op_sel_hi:[1,0]
	v_pk_mul_f32 v[70:71], v[70:71], s[4:5] op_sel_hi:[1,0]
	v_pk_mul_f32 v[72:73], v[72:73], s[4:5] op_sel_hi:[1,0]
	v_pk_mul_f32 v[74:75], v[74:75], s[4:5] op_sel_hi:[1,0]
	v_pk_mul_f32 v[76:77], v[76:77], s[4:5] op_sel_hi:[1,0]
	v_pk_mul_f32 v[78:79], v[78:79], s[4:5] op_sel_hi:[1,0]
	v_pk_mul_f32 v[64:65], v[64:65], v[112:113]
	v_pk_mul_f32 v[66:67], v[66:67], v[114:115]
	v_pk_mul_f32 v[68:69], v[68:69], v[116:117]
	v_pk_mul_f32 v[70:71], v[70:71], v[118:119]
	v_pk_mul_f32 v[72:73], v[72:73], v[120:121]
	v_pk_mul_f32 v[74:75], v[74:75], v[122:123]
	v_pk_mul_f32 v[76:77], v[76:77], v[124:125]
	v_pk_mul_f32 v[78:79], v[78:79], v[126:127]
	v_cvt_pk_bf16_f32 v38, v64, v65
	v_cvt_pk_bf16_f32 v39, v66, v67
	v_cvt_pk_bf16_f32 v40, v68, v69
	v_cvt_pk_bf16_f32 v41, v70, v71
	v_cvt_pk_bf16_f32 v42, v72, v73
	v_cvt_pk_bf16_f32 v43, v74, v75
	v_cvt_pk_bf16_f32 v44, v76, v77
	v_cvt_pk_bf16_f32 v45, v78, v79
	global_store_dwordx2 v3, v[38:39], s[12:13] offset:0
	global_store_dwordx2 v3, v[40:41], s[12:13] offset:512
	global_store_dwordx2 v3, v[42:43], s[12:13] offset:1024
	global_store_dwordx2 v3, v[44:45], s[12:13] offset:1536
	v_pk_mul_f32 v[16:17], v[64:65], v[128:129]
	v_pk_mul_f32 v[18:19], v[64:65], v[144:145]
	v_pk_mul_f32 v[20:21], v[64:65], v[160:161]
	v_pk_mul_f32 v[22:23], v[64:65], v[176:177]
	v_pk_mul_f32 v[24:25], v[64:65], v[192:193]
	v_pk_mul_f32 v[26:27], v[64:65], v[208:209]
	v_pk_mul_f32 v[28:29], v[64:65], v[224:225]
	v_pk_mul_f32 v[30:31], v[64:65], v[240:241]
	v_pk_fma_f32 v[16:17], v[66:67], v[130:131], v[16:17]
	v_pk_fma_f32 v[18:19], v[66:67], v[146:147], v[18:19]
	v_pk_fma_f32 v[20:21], v[66:67], v[162:163], v[20:21]
	v_pk_fma_f32 v[22:23], v[66:67], v[178:179], v[22:23]
	v_pk_fma_f32 v[24:25], v[66:67], v[194:195], v[24:25]
	v_pk_fma_f32 v[26:27], v[66:67], v[210:211], v[26:27]
	v_pk_fma_f32 v[28:29], v[66:67], v[226:227], v[28:29]
	v_pk_fma_f32 v[30:31], v[66:67], v[242:243], v[30:31]
	v_pk_fma_f32 v[16:17], v[68:69], v[132:133], v[16:17]
	v_pk_fma_f32 v[18:19], v[68:69], v[148:149], v[18:19]
	v_pk_fma_f32 v[20:21], v[68:69], v[164:165], v[20:21]
	v_pk_fma_f32 v[22:23], v[68:69], v[180:181], v[22:23]
	v_pk_fma_f32 v[24:25], v[68:69], v[196:197], v[24:25]
	v_pk_fma_f32 v[26:27], v[68:69], v[212:213], v[26:27]
	v_pk_fma_f32 v[28:29], v[68:69], v[228:229], v[28:29]
	v_pk_fma_f32 v[30:31], v[68:69], v[244:245], v[30:31]
	v_pk_fma_f32 v[16:17], v[70:71], v[134:135], v[16:17]
	v_pk_fma_f32 v[18:19], v[70:71], v[150:151], v[18:19]
	v_pk_fma_f32 v[20:21], v[70:71], v[166:167], v[20:21]
	v_pk_fma_f32 v[22:23], v[70:71], v[182:183], v[22:23]
	v_pk_fma_f32 v[24:25], v[70:71], v[198:199], v[24:25]
	v_pk_fma_f32 v[26:27], v[70:71], v[214:215], v[26:27]
	v_pk_fma_f32 v[28:29], v[70:71], v[230:231], v[28:29]
	v_pk_fma_f32 v[30:31], v[70:71], v[246:247], v[30:31]
	v_pk_fma_f32 v[16:17], v[72:73], v[136:137], v[16:17]
	v_pk_fma_f32 v[18:19], v[72:73], v[152:153], v[18:19]
	v_pk_fma_f32 v[20:21], v[72:73], v[168:169], v[20:21]
	v_pk_fma_f32 v[22:23], v[72:73], v[184:185], v[22:23]
	v_pk_fma_f32 v[24:25], v[72:73], v[200:201], v[24:25]
	v_pk_fma_f32 v[26:27], v[72:73], v[216:217], v[26:27]
	v_pk_fma_f32 v[28:29], v[72:73], v[232:233], v[28:29]
	v_pk_fma_f32 v[30:31], v[72:73], v[248:249], v[30:31]
	v_pk_fma_f32 v[16:17], v[74:75], v[138:139], v[16:17]
	v_pk_fma_f32 v[18:19], v[74:75], v[154:155], v[18:19]
	v_pk_fma_f32 v[20:21], v[74:75], v[170:171], v[20:21]
	v_pk_fma_f32 v[22:23], v[74:75], v[186:187], v[22:23]
	v_pk_fma_f32 v[24:25], v[74:75], v[202:203], v[24:25]
	v_pk_fma_f32 v[26:27], v[74:75], v[218:219], v[26:27]
	v_pk_fma_f32 v[28:29], v[74:75], v[234:235], v[28:29]
	v_pk_fma_f32 v[30:31], v[74:75], v[250:251], v[30:31]
; #define LAS __attribute__((address_space(3)))
; __device__ __forceinline__ void p0_prologue(const Args& a, LAS unsigned char* lds, int vcu, int G, int tid, int lane, int wave) {
;     ...
;         for (int h = 0; h < 8; ++h) { float acc = 0.f;
; #pragma unroll
;             for (int j = 0; j < 4; ++j) { const f32x4 w = *(const LAS f32x4*)(wf + h * 1024 + 256 * j + 4 * lane); acc += (v[j].x * w.x + v[j].y * w.y) + (v[j].z * w.z + v[j].w * w.w); }
;             f[h] = wave_sum(acc); }
;         float fz = f[0];
; #pragma unroll
;         for (int h = 1; h < 8; ++h) fz = (lane == h) ? f[h] : fz;
	v_pk_fma_f32 v[16:17], v[76:77], v[140:141], v[16:17]
	v_pk_fma_f32 v[18:19], v[76:77], v[156:157], v[18:19]
	v_pk_fma_f32 v[20:21], v[76:77], v[172:173], v[20:21]
	v_pk_fma_f32 v[22:23], v[76:77], v[188:189], v[22:23]
	v_pk_fma_f32 v[24:25], v[76:77], v[204:205], v[24:25]
	v_pk_fma_f32 v[26:27], v[76:77], v[220:221], v[26:27]
	v_pk_fma_f32 v[28:29], v[76:77], v[236:237], v[28:29]
	v_pk_fma_f32 v[30:31], v[76:77], v[252:253], v[30:31]
	v_pk_fma_f32 v[16:17], v[78:79], v[142:143], v[16:17]
	v_pk_fma_f32 v[18:19], v[78:79], v[158:159], v[18:19]
	v_pk_fma_f32 v[20:21], v[78:79], v[174:175], v[20:21]
	v_pk_fma_f32 v[22:23], v[78:79], v[190:191], v[22:23]
	v_pk_fma_f32 v[24:25], v[78:79], v[206:207], v[24:25]
	v_pk_fma_f32 v[26:27], v[78:79], v[222:223], v[26:27]
	v_pk_fma_f32 v[28:29], v[78:79], v[238:239], v[28:29]
	v_pk_fma_f32 v[30:31], v[78:79], v[254:255], v[30:31]
	v_add_f32_e32 v16, v16, v17
	v_add_f32_e32 v18, v18, v19
	v_add_f32_e32 v20, v20, v21
	v_add_f32_e32 v22, v22, v23
	v_add_f32_e32 v24, v24, v25
	v_add_f32_e32 v26, v26, v27
	v_add_f32_e32 v28, v28, v29
	v_add_f32_e32 v30, v30, v31
	v_add_f32_dpp v16, v16, v16 quad_perm:[1,0,3,2] row_mask:0xf bank_mask:0xf
	v_add_f32_dpp v18, v18, v18 quad_perm:[1,0,3,2] row_mask:0xf bank_mask:0xf
	v_add_f32_dpp v20, v20, v20 quad_perm:[1,0,3,2] row_mask:0xf bank_mask:0xf
	v_add_f32_dpp v22, v22, v22 quad_perm:[1,0,3,2] row_mask:0xf bank_mask:0xf
	v_add_f32_dpp v24, v24, v24 quad_perm:[1,0,3,2] row_mask:0xf bank_mask:0xf
	v_add_f32_dpp v26, v26, v26 quad_perm:[1,0,3,2] row_mask:0xf bank_mask:0xf
	v_add_f32_dpp v28, v28, v28 quad_perm:[1,0,3,2] row_mask:0xf bank_mask:0xf
	v_add_f32_dpp v30, v30, v30 quad_perm:[1,0,3,2] row_mask:0xf bank_mask:0xf
	v_add_f32_dpp v16, v16, v16 quad_perm:[2,3,0,1] row_mask:0xf bank_mask:0xf
	v_add_f32_dpp v18, v18, v18 quad_perm:[2,3,0,1] row_mask:0xf bank_mask:0xf
	v_add_f32_dpp v20, v20, v20 quad_perm:[2,3,0,1] row_mask:0xf bank_mask:0xf
	v_add_f32_dpp v22, v22, v22 quad_perm:[2,3,0,1] row_mask:0xf bank_mask:0xf
	v_add_f32_dpp v24, v24, v24 quad_perm:[2,3,0,1] row_mask:0xf bank_mask:0xf
	v_add_f32_dpp v26, v26, v26 quad_perm:[2,3,0,1] row_mask:0xf bank_mask:0xf
	v_add_f32_dpp v28, v28, v28 quad_perm:[2,3,0,1] row_mask:0xf bank_mask:0xf
	v_add_f32_dpp v30, v30, v30 quad_perm:[2,3,0,1] row_mask:0xf bank_mask:0xf
	v_add_f32_dpp v16, v16, v16 row_half_mirror row_mask:0xf bank_mask:0xf
	v_add_f32_dpp v18, v18, v18 row_half_mirror row_mask:0xf bank_mask:0xf
	v_add_f32_dpp v20, v20, v20 row_half_mirror row_mask:0xf bank_mask:0xf
	v_add_f32_dpp v22, v22, v22 row_half_mirror row_mask:0xf bank_mask:0xf
	v_add_f32_dpp v24, v24, v24 row_half_mirror row_mask:0xf bank_mask:0xf
	v_add_f32_dpp v26, v26, v26 row_half_mirror row_mask:0xf bank_mask:0xf
	v_add_f32_dpp v28, v28, v28 row_half_mirror row_mask:0xf bank_mask:0xf
	v_add_f32_dpp v30, v30, v30 row_half_mirror row_mask:0xf bank_mask:0xf
	v_add_f32_dpp v16, v16, v16 row_mirror row_mask:0xf bank_mask:0xf
	v_add_f32_dpp v18, v18, v18 row_mirror row_mask:0xf bank_mask:0xf
	v_add_f32_dpp v20, v20, v20 row_mirror row_mask:0xf bank_mask:0xf
	v_add_f32_dpp v22, v22, v22 row_mirror row_mask:0xf bank_mask:0xf
	v_add_f32_dpp v24, v24, v24 row_mirror row_mask:0xf bank_mask:0xf
	v_add_f32_dpp v26, v26, v26 row_mirror row_mask:0xf bank_mask:0xf
	v_add_f32_dpp v28, v28, v28 row_mirror row_mask:0xf bank_mask:0xf
	v_add_f32_dpp v30, v30, v30 row_mirror row_mask:0xf bank_mask:0xf
	v_add_f32_dpp v16, v16, v16 row_bcast:15 row_mask:0xa bank_mask:0xf
	v_add_f32_dpp v18, v18, v18 row_bcast:15 row_mask:0xa bank_mask:0xf
	v_add_f32_dpp v20, v20, v20 row_bcast:15 row_mask:0xa bank_mask:0xf
	v_add_f32_dpp v22, v22, v22 row_bcast:15 row_mask:0xa bank_mask:0xf
	v_add_f32_dpp v24, v24, v24 row_bcast:15 row_mask:0xa bank_mask:0xf
	v_add_f32_dpp v26, v26, v26 row_bcast:15 row_mask:0xa bank_mask:0xf
	v_add_f32_dpp v28, v28, v28 row_bcast:15 row_mask:0xa bank_mask:0xf
	v_add_f32_dpp v30, v30, v30 row_bcast:15 row_mask:0xa bank_mask:0xf
	v_add_f32_dpp v16, v16, v16 row_bcast:31 row_mask:0xc bank_mask:0xf
	v_add_f32_dpp v18, v18, v18 row_bcast:31 row_mask:0xc bank_mask:0xf
	v_add_f32_dpp v20, v20, v20 row_bcast:31 row_mask:0xc bank_mask:0xf
	v_add_f32_dpp v22, v22, v22 row_bcast:31 row_mask:0xc bank_mask:0xf
	v_add_f32_dpp v24, v24, v24 row_bcast:31 row_mask:0xc bank_mask:0xf
	v_add_f32_dpp v26, v26, v26 row_bcast:31 row_mask:0xc bank_mask:0xf
	v_add_f32_dpp v28, v28, v28 row_bcast:31 row_mask:0xc bank_mask:0xf
	v_add_f32_dpp v30, v30, v30 row_bcast:31 row_mask:0xc bank_mask:0xf
	s_nop 0
	v_readlane_b32 s14, v16, 63
	v_readlane_b32 s15, v18, 63
	v_readlane_b32 s16, v20, 63
	v_readlane_b32 s17, v22, 63
	v_readlane_b32 s18, v24, 63
	v_readlane_b32 s19, v26, 63
	v_readlane_b32 s46, v28, 63
	v_readlane_b32 s47, v30, 63
	s_nop 1
	v_writelane_b32 v4, s14, 40
	v_writelane_b32 v4, s15, 41
	v_writelane_b32 v4, s16, 42
	v_writelane_b32 v4, s17, 43
	v_writelane_b32 v4, s18, 44
	v_writelane_b32 v4, s19, 45
	v_writelane_b32 v4, s46, 46
	v_writelane_b32 v4, s47, 47
	s_mov_b32 s62, s8
	s_cmp_lt_i32 s8, 32768
	s_cbranch_scc1 .Lp0r_row6
	s_movk_i32 s6, 48
	s_branch .Lp0r_flush

; #define GAS __attribute__((address_space(1)))
; #define LAS __attribute__((address_space(3)))
; __device__ __forceinline__ unsigned pk2(float lo, float hi) { return pg8::cvt_pk_bf16_c(lo, hi); }
; __device__ __forceinline__ void p0_prologue(const Args& a, LAS unsigned char* lds, int vcu, int G, int tid, int lane, int wave) {
;     ...
;     for (int m = gw; m < T; m += NGW) {
;         f32x4 v[4]; float s2 = 0.f;
; #pragma unroll
;         for (int j = 0; j < 4; ++j) { v[j] = nv[j]; s2 += (v[j].x * v[j].x + v[j].y * v[j].y) + (v[j].z * v[j].z + v[j].w * v[j].w); }
;         if (m + NGW < T) { const GAS f32x4* xr = (const GAS f32x4*)(x + (size_t)(m + NGW) * DM) + lane;
; #pragma unroll
;             for (int j = 0; j < 4; ++j) nv[j] = xr[64 * j]; }
;         const float rstd = 1.0f / sqrtf(wave_sum(s2) * (1.f / DM) + EPS);
; #pragma unroll
;         for (int j = 0; j < 4; ++j) v[j] = v[j] * rstd * gv[j];
;         GAS unsigned long long* o8 = (GAS unsigned long long*)(XN + (size_t)m * DM) + lane;
; #pragma unroll
;         for (int j = 0; j < 4; ++j) o8[64 * j] = (unsigned long long)pk2(v[j].x, v[j].y) | ((unsigned long long)pk2(v[j].z, v[j].w) << 32);
;         float f[8];
; #pragma unroll
;         for (int h = 0; h < 8; ++h) { float acc = 0.f;
; #pragma unroll
;             for (int j = 0; j < 4; ++j) { const f32x4 w = *(const LAS f32x4*)(wf + h * 1024 + 256 * j + 4 * lane); acc += (v[j].x * w.x + v[j].y * w.y) + (v[j].z * w.z + v[j].w * w.w); }
.Lp0r_nl_6:
	v_pk_mul_f32 v[10:11], v[80:81], v[80:81]
	v_pk_mul_f32 v[12:13], v[82:83], v[82:83]
	v_pk_fma_f32 v[10:11], v[84:85], v[84:85], v[10:11]
	v_pk_fma_f32 v[12:13], v[86:87], v[86:87], v[12:13]
	v_pk_fma_f32 v[10:11], v[88:89], v[88:89], v[10:11]
	v_pk_fma_f32 v[12:13], v[90:91], v[90:91], v[12:13]
	v_pk_fma_f32 v[10:11], v[92:93], v[92:93], v[10:11]
	v_pk_fma_f32 v[12:13], v[94:95], v[94:95], v[12:13]
	s_lshl_b32 s12, s62, 11
	v_pk_add_f32 v[10:11], v[10:11], v[12:13]
	s_add_u32 s12, s26, s12
	s_addc_u32 s13, s27, 0
	v_add_f32_e32 v6, v10, v11
	s_nop 1
	v_add_f32_dpp v6, v6, v6 quad_perm:[1,0,3,2] row_mask:0xf bank_mask:0xf
	s_nop 1
	v_add_f32_dpp v6, v6, v6 quad_perm:[2,3,0,1] row_mask:0xf bank_mask:0xf
	s_nop 1
	v_add_f32_dpp v6, v6, v6 row_half_mirror row_mask:0xf bank_mask:0xf
	s_nop 1
	v_add_f32_dpp v6, v6, v6 row_mirror row_mask:0xf bank_mask:0xf
	s_nop 1
	v_add_f32_dpp v6, v6, v6 row_bcast:15 row_mask:0xa bank_mask:0xf
	s_nop 1
	v_add_f32_dpp v6, v6, v6 row_bcast:31 row_mask:0xc bank_mask:0xf
	v_mov_b32_e32 v7, 0x358637bd
	s_nop 0
	v_fmamk_f32 v6, v6, 0x3a800000, v7
	s_nop 0
	v_rsq_f32_e32 v7, v6
	v_mul_f32_e32 v6, 0.5, v6
	s_nop 0
	v_mul_f32_e32 v6, v6, v7
	s_nop 0
	v_fma_f32 v6, -v6, v7, 0.5
	s_nop 0
	v_fma_f32 v7, v7, v6, v7
	s_nop 1
	v_readlane_b32 s4, v7, 63
	s_nop 3
	v_pk_mul_f32 v[80:81], v[80:81], s[4:5] op_sel_hi:[1,0]
	v_pk_mul_f32 v[82:83], v[82:83], s[4:5] op_sel_hi:[1,0]
	v_pk_mul_f32 v[84:85], v[84:85], s[4:5] op_sel_hi:[1,0]
	v_pk_mul_f32 v[86:87], v[86:87], s[4:5] op_sel_hi:[1,0]
	v_pk_mul_f32 v[88:89], v[88:89], s[4:5] op_sel_hi:[1,0]
	v_pk_mul_f32 v[90:91], v[90:91], s[4:5] op_sel_hi:[1,0]
	v_pk_mul_f32 v[92:93], v[92:93], s[4:5] op_sel_hi:[1,0]
	v_pk_mul_f32 v[94:95], v[94:95], s[4:5] op_sel_hi:[1,0]
	v_pk_mul_f32 v[80:81], v[80:81], v[112:113]
	v_pk_mul_f32 v[82:83], v[82:83], v[114:115]
	v_pk_mul_f32 v[84:85], v[84:85], v[116:117]
	v_pk_mul_f32 v[86:87], v[86:87], v[118:119]
	v_pk_mul_f32 v[88:89], v[88:89], v[120:121]
	v_pk_mul_f32 v[90:91], v[90:91], v[122:123]
	v_pk_mul_f32 v[92:93], v[92:93], v[124:125]
	v_pk_mul_f32 v[94:95], v[94:95], v[126:127]
	v_cvt_pk_bf16_f32 v38, v80, v81
	v_cvt_pk_bf16_f32 v39, v82, v83
	v_cvt_pk_bf16_f32 v40, v84, v85
	v_cvt_pk_bf16_f32 v41, v86, v87
	v_cvt_pk_bf16_f32 v42, v88, v89
	v_cvt_pk_bf16_f32 v43, v90, v91
	v_cvt_pk_bf16_f32 v44, v92, v93
	v_cvt_pk_bf16_f32 v45, v94, v95
	global_store_dwordx2 v3, v[38:39], s[12:13] offset:0
	global_store_dwordx2 v3, v[40:41], s[12:13] offset:512
	global_store_dwordx2 v3, v[42:43], s[12:13] offset:1024
	global_store_dwordx2 v3, v[44:45], s[12:13] offset:1536
	v_pk_mul_f32 v[16:17], v[80:81], v[128:129]
	v_pk_mul_f32 v[18:19], v[80:81], v[144:145]
	v_pk_mul_f32 v[20:21], v[80:81], v[160:161]
	v_pk_mul_f32 v[22:23], v[80:81], v[176:177]
	v_pk_mul_f32 v[24:25], v[80:81], v[192:193]
	v_pk_mul_f32 v[26:27], v[80:81], v[208:209]
	v_pk_mul_f32 v[28:29], v[80:81], v[224:225]
	v_pk_mul_f32 v[30:31], v[80:81], v[240:241]
	v_pk_fma_f32 v[16:17], v[82:83], v[130:131], v[16:17]
	v_pk_fma_f32 v[18:19], v[82:83], v[146:147], v[18:19]
	v_pk_fma_f32 v[20:21], v[82:83], v[162:163], v[20:21]
	v_pk_fma_f32 v[22:23], v[82:83], v[178:179], v[22:23]
	v_pk_fma_f32 v[24:25], v[82:83], v[194:195], v[24:25]
	v_pk_fma_f32 v[26:27], v[82:83], v[210:211], v[26:27]
	v_pk_fma_f32 v[28:29], v[82:83], v[226:227], v[28:29]
	v_pk_fma_f32 v[30:31], v[82:83], v[242:243], v[30:31]
	v_pk_fma_f32 v[16:17], v[84:85], v[132:133], v[16:17]
	v_pk_fma_f32 v[18:19], v[84:85], v[148:149], v[18:19]
	v_pk_fma_f32 v[20:21], v[84:85], v[164:165], v[20:21]
	v_pk_fma_f32 v[22:23], v[84:85], v[180:181], v[22:23]
	v_pk_fma_f32 v[24:25], v[84:85], v[196:197], v[24:25]
	v_pk_fma_f32 v[26:27], v[84:85], v[212:213], v[26:27]
	v_pk_fma_f32 v[28:29], v[84:85], v[228:229], v[28:29]
	v_pk_fma_f32 v[30:31], v[84:85], v[244:245], v[30:31]
	v_pk_fma_f32 v[16:17], v[86:87], v[134:135], v[16:17]
	v_pk_fma_f32 v[18:19], v[86:87], v[150:151], v[18:19]
	v_pk_fma_f32 v[20:21], v[86:87], v[166:167], v[20:21]
	v_pk_fma_f32 v[22:23], v[86:87], v[182:183], v[22:23]
	v_pk_fma_f32 v[24:25], v[86:87], v[198:199], v[24:25]
	v_pk_fma_f32 v[26:27], v[86:87], v[214:215], v[26:27]
	v_pk_fma_f32 v[28:29], v[86:87], v[230:231], v[28:29]
	v_pk_fma_f32 v[30:31], v[86:87], v[246:247], v[30:31]
	v_pk_fma_f32 v[16:17], v[88:89], v[136:137], v[16:17]
	v_pk_fma_f32 v[18:19], v[88:89], v[152:153], v[18:19]
	v_pk_fma_f32 v[20:21], v[88:89], v[168:169], v[20:21]
	v_pk_fma_f32 v[22:23], v[88:89], v[184:185], v[22:23]
	v_pk_fma_f32 v[24:25], v[88:89], v[200:201], v[24:25]
	v_pk_fma_f32 v[26:27], v[88:89], v[216:217], v[26:27]
	v_pk_fma_f32 v[28:29], v[88:89], v[232:233], v[28:29]
	v_pk_fma_f32 v[30:31], v[88:89], v[248:249], v[30:31]
	v_pk_fma_f32 v[16:17], v[90:91], v[138:139], v[16:17]
	v_pk_fma_f32 v[18:19], v[90:91], v[154:155], v[18:19]
	v_pk_fma_f32 v[20:21], v[90:91], v[170:171], v[20:21]
	v_pk_fma_f32 v[22:23], v[90:91], v[186:187], v[22:23]
	v_pk_fma_f32 v[24:25], v[90:91], v[202:203], v[24:25]
	v_pk_fma_f32 v[26:27], v[90:91], v[218:219], v[26:27]
	v_pk_fma_f32 v[28:29], v[90:91], v[234:235], v[28:29]
	v_pk_fma_f32 v[30:31], v[90:91], v[250:251], v[30:31]
; #define LAS __attribute__((address_space(3)))
; __device__ __forceinline__ void p0_prologue(const Args& a, LAS unsigned char* lds, int vcu, int G, int tid, int lane, int wave) {
;     ...
;         for (int h = 0; h < 8; ++h) { float acc = 0.f;
; #pragma unroll
;             for (int j = 0; j < 4; ++j) { const f32x4 w = *(const LAS f32x4*)(wf + h * 1024 + 256 * j + 4 * lane); acc += (v[j].x * w.x + v[j].y * w.y) + (v[j].z * w.z + v[j].w * w.w); }
;             f[h] = wave_sum(acc); }
;         float fz = f[0];
; #pragma unroll
;         for (int h = 1; h < 8; ++h) fz = (lane == h) ? f[h] : fz;
	v_pk_fma_f32 v[16:17], v[92:93], v[140:141], v[16:17]
	v_pk_fma_f32 v[18:19], v[92:93], v[156:157], v[18:19]
	v_pk_fma_f32 v[20:21], v[92:93], v[172:173], v[20:21]
	v_pk_fma_f32 v[22:23], v[92:93], v[188:189], v[22:23]
	v_pk_fma_f32 v[24:25], v[92:93], v[204:205], v[24:25]
	v_pk_fma_f32 v[26:27], v[92:93], v[220:221], v[26:27]
	v_pk_fma_f32 v[28:29], v[92:93], v[236:237], v[28:29]
	v_pk_fma_f32 v[30:31], v[92:93], v[252:253], v[30:31]
	v_pk_fma_f32 v[16:17], v[94:95], v[142:143], v[16:17]
	v_pk_fma_f32 v[18:19], v[94:95], v[158:159], v[18:19]
	v_pk_fma_f32 v[20:21], v[94:95], v[174:175], v[20:21]
	v_pk_fma_f32 v[22:23], v[94:95], v[190:191], v[22:23]
	v_pk_fma_f32 v[24:25], v[94:95], v[206:207], v[24:25]
	v_pk_fma_f32 v[26:27], v[94:95], v[222:223], v[26:27]
	v_pk_fma_f32 v[28:29], v[94:95], v[238:239], v[28:29]
	v_pk_fma_f32 v[30:31], v[94:95], v[254:255], v[30:31]
	v_add_f32_e32 v16, v16, v17
	v_add_f32_e32 v18, v18, v19
	v_add_f32_e32 v20, v20, v21
	v_add_f32_e32 v22, v22, v23
	v_add_f32_e32 v24, v24, v25
	v_add_f32_e32 v26, v26, v27
	v_add_f32_e32 v28, v28, v29
	v_add_f32_e32 v30, v30, v31
	v_add_f32_dpp v16, v16, v16 quad_perm:[1,0,3,2] row_mask:0xf bank_mask:0xf
	v_add_f32_dpp v18, v18, v18 quad_perm:[1,0,3,2] row_mask:0xf bank_mask:0xf
	v_add_f32_dpp v20, v20, v20 quad_perm:[1,0,3,2] row_mask:0xf bank_mask:0xf
	v_add_f32_dpp v22, v22, v22 quad_perm:[1,0,3,2] row_mask:0xf bank_mask:0xf
	v_add_f32_dpp v24, v24, v24 quad_perm:[1,0,3,2] row_mask:0xf bank_mask:0xf
	v_add_f32_dpp v26, v26, v26 quad_perm:[1,0,3,2] row_mask:0xf bank_mask:0xf
	v_add_f32_dpp v28, v28, v28 quad_perm:[1,0,3,2] row_mask:0xf bank_mask:0xf
	v_add_f32_dpp v30, v30, v30 quad_perm:[1,0,3,2] row_mask:0xf bank_mask:0xf
	v_add_f32_dpp v16, v16, v16 quad_perm:[2,3,0,1] row_mask:0xf bank_mask:0xf
	v_add_f32_dpp v18, v18, v18 quad_perm:[2,3,0,1] row_mask:0xf bank_mask:0xf
	v_add_f32_dpp v20, v20, v20 quad_perm:[2,3,0,1] row_mask:0xf bank_mask:0xf
	v_add_f32_dpp v22, v22, v22 quad_perm:[2,3,0,1] row_mask:0xf bank_mask:0xf
	v_add_f32_dpp v24, v24, v24 quad_perm:[2,3,0,1] row_mask:0xf bank_mask:0xf
	v_add_f32_dpp v26, v26, v26 quad_perm:[2,3,0,1] row_mask:0xf bank_mask:0xf
	v_add_f32_dpp v28, v28, v28 quad_perm:[2,3,0,1] row_mask:0xf bank_mask:0xf
	v_add_f32_dpp v30, v30, v30 quad_perm:[2,3,0,1] row_mask:0xf bank_mask:0xf
	v_add_f32_dpp v16, v16, v16 row_half_mirror row_mask:0xf bank_mask:0xf
	v_add_f32_dpp v18, v18, v18 row_half_mirror row_mask:0xf bank_mask:0xf
	v_add_f32_dpp v20, v20, v20 row_half_mirror row_mask:0xf bank_mask:0xf
	v_add_f32_dpp v22, v22, v22 row_half_mirror row_mask:0xf bank_mask:0xf
	v_add_f32_dpp v24, v24, v24 row_half_mirror row_mask:0xf bank_mask:0xf
	v_add_f32_dpp v26, v26, v26 row_half_mirror row_mask:0xf bank_mask:0xf
	v_add_f32_dpp v28, v28, v28 row_half_mirror row_mask:0xf bank_mask:0xf
	v_add_f32_dpp v30, v30, v30 row_half_mirror row_mask:0xf bank_mask:0xf
	v_add_f32_dpp v16, v16, v16 row_mirror row_mask:0xf bank_mask:0xf
	v_add_f32_dpp v18, v18, v18 row_mirror row_mask:0xf bank_mask:0xf
	v_add_f32_dpp v20, v20, v20 row_mirror row_mask:0xf bank_mask:0xf
	v_add_f32_dpp v22, v22, v22 row_mirror row_mask:0xf bank_mask:0xf
	v_add_f32_dpp v24, v24, v24 row_mirror row_mask:0xf bank_mask:0xf
	v_add_f32_dpp v26, v26, v26 row_mirror row_mask:0xf bank_mask:0xf
	v_add_f32_dpp v28, v28, v28 row_mirror row_mask:0xf bank_mask:0xf
	v_add_f32_dpp v30, v30, v30 row_mirror row_mask:0xf bank_mask:0xf
	v_add_f32_dpp v16, v16, v16 row_bcast:15 row_mask:0xa bank_mask:0xf
	v_add_f32_dpp v18, v18, v18 row_bcast:15 row_mask:0xa bank_mask:0xf
	v_add_f32_dpp v20, v20, v20 row_bcast:15 row_mask:0xa bank_mask:0xf
	v_add_f32_dpp v22, v22, v22 row_bcast:15 row_mask:0xa bank_mask:0xf
	v_add_f32_dpp v24, v24, v24 row_bcast:15 row_mask:0xa bank_mask:0xf
	v_add_f32_dpp v26, v26, v26 row_bcast:15 row_mask:0xa bank_mask:0xf
	v_add_f32_dpp v28, v28, v28 row_bcast:15 row_mask:0xa bank_mask:0xf
	v_add_f32_dpp v30, v30, v30 row_bcast:15 row_mask:0xa bank_mask:0xf
	v_add_f32_dpp v16, v16, v16 row_bcast:31 row_mask:0xc bank_mask:0xf
	v_add_f32_dpp v18, v18, v18 row_bcast:31 row_mask:0xc bank_mask:0xf
	v_add_f32_dpp v20, v20, v20 row_bcast:31 row_mask:0xc bank_mask:0xf
	v_add_f32_dpp v22, v22, v22 row_bcast:31 row_mask:0xc bank_mask:0xf
	v_add_f32_dpp v24, v24, v24 row_bcast:31 row_mask:0xc bank_mask:0xf
	v_add_f32_dpp v26, v26, v26 row_bcast:31 row_mask:0xc bank_mask:0xf
	v_add_f32_dpp v28, v28, v28 row_bcast:31 row_mask:0xc bank_mask:0xf
	v_add_f32_dpp v30, v30, v30 row_bcast:31 row_mask:0xc bank_mask:0xf
	s_nop 0
	v_readlane_b32 s14, v16, 63
	v_readlane_b32 s15, v18, 63
	v_readlane_b32 s16, v20, 63
	v_readlane_b32 s17, v22, 63
	v_readlane_b32 s18, v24, 63
	v_readlane_b32 s19, v26, 63
	v_readlane_b32 s46, v28, 63
	v_readlane_b32 s47, v30, 63
	s_nop 1
	v_writelane_b32 v4, s14, 48
	v_writelane_b32 v4, s15, 49
	v_writelane_b32 v4, s16, 50
	v_writelane_b32 v4, s17, 51
	v_writelane_b32 v4, s18, 52
	v_writelane_b32 v4, s19, 53
	v_writelane_b32 v4, s46, 54
	v_writelane_b32 v4, s47, 55
	s_mov_b32 s62, s8
	s_cmp_lt_i32 s8, 32768
	s_cbranch_scc1 .Lp0r_row7
	s_movk_i32 s6, 56
	s_branch .Lp0r_flush

; #define GAS __attribute__((address_space(1)))
; #define LAS __attribute__((address_space(3)))
; __device__ __forceinline__ unsigned pk2(float lo, float hi) { return pg8::cvt_pk_bf16_c(lo, hi); }
; __device__ __forceinline__ void p0_prologue(const Args& a, LAS unsigned char* lds, int vcu, int G, int tid, int lane, int wave) {
;     ...
;     for (int m = gw; m < T; m += NGW) {
;         f32x4 v[4]; float s2 = 0.f;
; #pragma unroll
;         for (int j = 0; j < 4; ++j) { v[j] = nv[j]; s2 += (v[j].x * v[j].x + v[j].y * v[j].y) + (v[j].z * v[j].z + v[j].w * v[j].w); }
;         if (m + NGW < T) { const GAS f32x4* xr = (const GAS f32x4*)(x + (size_t)(m + NGW) * DM) + lane;
; #pragma unroll
;             for (int j = 0; j < 4; ++j) nv[j] = xr[64 * j]; }
;         const float rstd = 1.0f / sqrtf(wave_sum(s2) * (1.f / DM) + EPS);
; #pragma unroll
;         for (int j = 0; j < 4; ++j) v[j] = v[j] * rstd * gv[j];
;         GAS unsigned long long* o8 = (GAS unsigned long long*)(XN + (size_t)m * DM) + lane;
; #pragma unroll
;         for (int j = 0; j < 4; ++j) o8[64 * j] = (unsigned long long)pk2(v[j].x, v[j].y) | ((unsigned long long)pk2(v[j].z, v[j].w) << 32);
;         float f[8];
; #pragma unroll
;         for (int h = 0; h < 8; ++h) { float acc = 0.f;
; #pragma unroll
;             for (int j = 0; j < 4; ++j) { const f32x4 w = *(const LAS f32x4*)(wf + h * 1024 + 256 * j + 4 * lane); acc += (v[j].x * w.x + v[j].y * w.y) + (v[j].z * w.z + v[j].w * w.w); }
.Lp0r_nl_7:
	v_pk_mul_f32 v[10:11], v[96:97], v[96:97]
	v_pk_mul_f32 v[12:13], v[98:99], v[98:99]
	v_pk_fma_f32 v[10:11], v[100:101], v[100:101], v[10:11]
	v_pk_fma_f32 v[12:13], v[102:103], v[102:103], v[12:13]
	v_pk_fma_f32 v[10:11], v[104:105], v[104:105], v[10:11]
	v_pk_fma_f32 v[12:13], v[106:107], v[106:107], v[12:13]
	v_pk_fma_f32 v[10:11], v[108:109], v[108:109], v[10:11]
	v_pk_fma_f32 v[12:13], v[110:111], v[110:111], v[12:13]
	s_lshl_b32 s12, s62, 11
	v_pk_add_f32 v[10:11], v[10:11], v[12:13]
	s_add_u32 s12, s26, s12
	s_addc_u32 s13, s27, 0
	v_add_f32_e32 v6, v10, v11
	s_nop 1
	v_add_f32_dpp v6, v6, v6 quad_perm:[1,0,3,2] row_mask:0xf bank_mask:0xf
	s_nop 1
	v_add_f32_dpp v6, v6, v6 quad_perm:[2,3,0,1] row_mask:0xf bank_mask:0xf
	s_nop 1
	v_add_f32_dpp v6, v6, v6 row_half_mirror row_mask:0xf bank_mask:0xf
	s_nop 1
	v_add_f32_dpp v6, v6, v6 row_mirror row_mask:0xf bank_mask:0xf
	s_nop 1
	v_add_f32_dpp v6, v6, v6 row_bcast:15 row_mask:0xa bank_mask:0xf
	s_nop 1
	v_add_f32_dpp v6, v6, v6 row_bcast:31 row_mask:0xc bank_mask:0xf
	v_mov_b32_e32 v7, 0x358637bd
	s_nop 0
	v_fmamk_f32 v6, v6, 0x3a800000, v7
	s_nop 0
	v_rsq_f32_e32 v7, v6
	v_mul_f32_e32 v6, 0.5, v6
	s_nop 0
	v_mul_f32_e32 v6, v6, v7
	s_nop 0
	v_fma_f32 v6, -v6, v7, 0.5
	s_nop 0
	v_fma_f32 v7, v7, v6, v7
	s_nop 1
	v_readlane_b32 s4, v7, 63
	s_nop 3
	v_pk_mul_f32 v[96:97], v[96:97], s[4:5] op_sel_hi:[1,0]
	v_pk_mul_f32 v[98:99], v[98:99], s[4:5] op_sel_hi:[1,0]
	v_pk_mul_f32 v[100:101], v[100:101], s[4:5] op_sel_hi:[1,0]
	v_pk_mul_f32 v[102:103], v[102:103], s[4:5] op_sel_hi:[1,0]
	v_pk_mul_f32 v[104:105], v[104:105], s[4:5] op_sel_hi:[1,0]
	v_pk_mul_f32 v[106:107], v[106:107], s[4:5] op_sel_hi:[1,0]
	v_pk_mul_f32 v[108:109], v[108:109], s[4:5] op_sel_hi:[1,0]
	v_pk_mul_f32 v[110:111], v[110:111], s[4:5] op_sel_hi:[1,0]
	v_pk_mul_f32 v[96:97], v[96:97], v[112:113]
	v_pk_mul_f32 v[98:99], v[98:99], v[114:115]
	v_pk_mul_f32 v[100:101], v[100:101], v[116:117]
	v_pk_mul_f32 v[102:103], v[102:103], v[118:119]
	v_pk_mul_f32 v[104:105], v[104:105], v[120:121]
	v_pk_mul_f32 v[106:107], v[106:107], v[122:123]
	v_pk_mul_f32 v[108:109], v[108:109], v[124:125]
	v_pk_mul_f32 v[110:111], v[110:111], v[126:127]
	v_cvt_pk_bf16_f32 v38, v96, v97
	v_cvt_pk_bf16_f32 v39, v98, v99
	v_cvt_pk_bf16_f32 v40, v100, v101
	v_cvt_pk_bf16_f32 v41, v102, v103
	v_cvt_pk_bf16_f32 v42, v104, v105
	v_cvt_pk_bf16_f32 v43, v106, v107
	v_cvt_pk_bf16_f32 v44, v108, v109
	v_cvt_pk_bf16_f32 v45, v110, v111
	global_store_dwordx2 v3, v[38:39], s[12:13] offset:0
	global_store_dwordx2 v3, v[40:41], s[12:13] offset:512
	global_store_dwordx2 v3, v[42:43], s[12:13] offset:1024
	global_store_dwordx2 v3, v[44:45], s[12:13] offset:1536
	v_pk_mul_f32 v[16:17], v[96:97], v[128:129]
	v_pk_mul_f32 v[18:19], v[96:97], v[144:145]
	v_pk_mul_f32 v[20:21], v[96:97], v[160:161]
	v_pk_mul_f32 v[22:23], v[96:97], v[176:177]
	v_pk_mul_f32 v[24:25], v[96:97], v[192:193]
	v_pk_mul_f32 v[26:27], v[96:97], v[208:209]
	v_pk_mul_f32 v[28:29], v[96:97], v[224:225]
	v_pk_mul_f32 v[30:31], v[96:97], v[240:241]
	v_pk_fma_f32 v[16:17], v[98:99], v[130:131], v[16:17]
	v_pk_fma_f32 v[18:19], v[98:99], v[146:147], v[18:19]
	v_pk_fma_f32 v[20:21], v[98:99], v[162:163], v[20:21]
	v_pk_fma_f32 v[22:23], v[98:99], v[178:179], v[22:23]
	v_pk_fma_f32 v[24:25], v[98:99], v[194:195], v[24:25]
	v_pk_fma_f32 v[26:27], v[98:99], v[210:211], v[26:27]
	v_pk_fma_f32 v[28:29], v[98:99], v[226:227], v[28:29]
	v_pk_fma_f32 v[30:31], v[98:99], v[242:243], v[30:31]
	v_pk_fma_f32 v[16:17], v[100:101], v[132:133], v[16:17]
	v_pk_fma_f32 v[18:19], v[100:101], v[148:149], v[18:19]
	v_pk_fma_f32 v[20:21], v[100:101], v[164:165], v[20:21]
	v_pk_fma_f32 v[22:23], v[100:101], v[180:181], v[22:23]
	v_pk_fma_f32 v[24:25], v[100:101], v[196:197], v[24:25]
	v_pk_fma_f32 v[26:27], v[100:101], v[212:213], v[26:27]
	v_pk_fma_f32 v[28:29], v[100:101], v[228:229], v[28:29]
	v_pk_fma_f32 v[30:31], v[100:101], v[244:245], v[30:31]
	v_pk_fma_f32 v[16:17], v[102:103], v[134:135], v[16:17]
	v_pk_fma_f32 v[18:19], v[102:103], v[150:151], v[18:19]
	v_pk_fma_f32 v[20:21], v[102:103], v[166:167], v[20:21]
	v_pk_fma_f32 v[22:23], v[102:103], v[182:183], v[22:23]
	v_pk_fma_f32 v[24:25], v[102:103], v[198:199], v[24:25]
	v_pk_fma_f32 v[26:27], v[102:103], v[214:215], v[26:27]
	v_pk_fma_f32 v[28:29], v[102:103], v[230:231], v[28:29]
	v_pk_fma_f32 v[30:31], v[102:103], v[246:247], v[30:31]
	v_pk_fma_f32 v[16:17], v[104:105], v[136:137], v[16:17]
	v_pk_fma_f32 v[18:19], v[104:105], v[152:153], v[18:19]
	v_pk_fma_f32 v[20:21], v[104:105], v[168:169], v[20:21]
	v_pk_fma_f32 v[22:23], v[104:105], v[184:185], v[22:23]
	v_pk_fma_f32 v[24:25], v[104:105], v[200:201], v[24:25]
	v_pk_fma_f32 v[26:27], v[104:105], v[216:217], v[26:27]
	v_pk_fma_f32 v[28:29], v[104:105], v[232:233], v[28:29]
	v_pk_fma_f32 v[30:31], v[104:105], v[248:249], v[30:31]
	v_pk_fma_f32 v[16:17], v[106:107], v[138:139], v[16:17]
	v_pk_fma_f32 v[18:19], v[106:107], v[154:155], v[18:19]
	v_pk_fma_f32 v[20:21], v[106:107], v[170:171], v[20:21]
	v_pk_fma_f32 v[22:23], v[106:107], v[186:187], v[22:23]
	v_pk_fma_f32 v[24:25], v[106:107], v[202:203], v[24:25]
	v_pk_fma_f32 v[26:27], v[106:107], v[218:219], v[26:27]
	v_pk_fma_f32 v[28:29], v[106:107], v[234:235], v[28:29]
	v_pk_fma_f32 v[30:31], v[106:107], v[250:251], v[30:31]
	v_pk_fma_f32 v[16:17], v[108:109], v[140:141], v[16:17]
	v_pk_fma_f32 v[18:19], v[108:109], v[156:157], v[18:19]
	v_pk_fma_f32 v[20:21], v[108:109], v[172:173], v[20:21]
	v_pk_fma_f32 v[22:23], v[108:109], v[188:189], v[22:23]
	v_pk_fma_f32 v[24:25], v[108:109], v[204:205], v[24:25]
	v_pk_fma_f32 v[26:27], v[108:109], v[220:221], v[26:27]
; #define LAS __attribute__((address_space(3)))
; __device__ __forceinline__ void p0_prologue(const Args& a, LAS unsigned char* lds, int vcu, int G, int tid, int lane, int wave) {
;     ...
;         for (int h = 0; h < 8; ++h) { float acc = 0.f;
; #pragma unroll
;             for (int j = 0; j < 4; ++j) { const f32x4 w = *(const LAS f32x4*)(wf + h * 1024 + 256 * j + 4 * lane); acc += (v[j].x * w.x + v[j].y * w.y) + (v[j].z * w.z + v[j].w * w.w); }
;             f[h] = wave_sum(acc); }
;         float fz = f[0];
; #pragma unroll
;         for (int h = 1; h < 8; ++h) fz = (lane == h) ? f[h] : fz;
	v_pk_fma_f32 v[28:29], v[108:109], v[236:237], v[28:29]
	v_pk_fma_f32 v[30:31], v[108:109], v[252:253], v[30:31]
	v_pk_fma_f32 v[16:17], v[110:111], v[142:143], v[16:17]
	v_pk_fma_f32 v[18:19], v[110:111], v[158:159], v[18:19]
	v_pk_fma_f32 v[20:21], v[110:111], v[174:175], v[20:21]
	v_pk_fma_f32 v[22:23], v[110:111], v[190:191], v[22:23]
	v_pk_fma_f32 v[24:25], v[110:111], v[206:207], v[24:25]
	v_pk_fma_f32 v[26:27], v[110:111], v[222:223], v[26:27]
	v_pk_fma_f32 v[28:29], v[110:111], v[238:239], v[28:29]
	v_pk_fma_f32 v[30:31], v[110:111], v[254:255], v[30:31]
	v_add_f32_e32 v16, v16, v17
	v_add_f32_e32 v18, v18, v19
	v_add_f32_e32 v20, v20, v21
	v_add_f32_e32 v22, v22, v23
	v_add_f32_e32 v24, v24, v25
	v_add_f32_e32 v26, v26, v27
	v_add_f32_e32 v28, v28, v29
	v_add_f32_e32 v30, v30, v31
	v_add_f32_dpp v16, v16, v16 quad_perm:[1,0,3,2] row_mask:0xf bank_mask:0xf
	v_add_f32_dpp v18, v18, v18 quad_perm:[1,0,3,2] row_mask:0xf bank_mask:0xf
	v_add_f32_dpp v20, v20, v20 quad_perm:[1,0,3,2] row_mask:0xf bank_mask:0xf
	v_add_f32_dpp v22, v22, v22 quad_perm:[1,0,3,2] row_mask:0xf bank_mask:0xf
	v_add_f32_dpp v24, v24, v24 quad_perm:[1,0,3,2] row_mask:0xf bank_mask:0xf
	v_add_f32_dpp v26, v26, v26 quad_perm:[1,0,3,2] row_mask:0xf bank_mask:0xf
	v_add_f32_dpp v28, v28, v28 quad_perm:[1,0,3,2] row_mask:0xf bank_mask:0xf
	v_add_f32_dpp v30, v30, v30 quad_perm:[1,0,3,2] row_mask:0xf bank_mask:0xf
	v_add_f32_dpp v16, v16, v16 quad_perm:[2,3,0,1] row_mask:0xf bank_mask:0xf
	v_add_f32_dpp v18, v18, v18 quad_perm:[2,3,0,1] row_mask:0xf bank_mask:0xf
	v_add_f32_dpp v20, v20, v20 quad_perm:[2,3,0,1] row_mask:0xf bank_mask:0xf
	v_add_f32_dpp v22, v22, v22 quad_perm:[2,3,0,1] row_mask:0xf bank_mask:0xf
	v_add_f32_dpp v24, v24, v24 quad_perm:[2,3,0,1] row_mask:0xf bank_mask:0xf
	v_add_f32_dpp v26, v26, v26 quad_perm:[2,3,0,1] row_mask:0xf bank_mask:0xf
	v_add_f32_dpp v28, v28, v28 quad_perm:[2,3,0,1] row_mask:0xf bank_mask:0xf
	v_add_f32_dpp v30, v30, v30 quad_perm:[2,3,0,1] row_mask:0xf bank_mask:0xf
	v_add_f32_dpp v16, v16, v16 row_half_mirror row_mask:0xf bank_mask:0xf
	v_add_f32_dpp v18, v18, v18 row_half_mirror row_mask:0xf bank_mask:0xf
	v_add_f32_dpp v20, v20, v20 row_half_mirror row_mask:0xf bank_mask:0xf
	v_add_f32_dpp v22, v22, v22 row_half_mirror row_mask:0xf bank_mask:0xf
	v_add_f32_dpp v24, v24, v24 row_half_mirror row_mask:0xf bank_mask:0xf
	v_add_f32_dpp v26, v26, v26 row_half_mirror row_mask:0xf bank_mask:0xf
	v_add_f32_dpp v28, v28, v28 row_half_mirror row_mask:0xf bank_mask:0xf
	v_add_f32_dpp v30, v30, v30 row_half_mirror row_mask:0xf bank_mask:0xf
	v_add_f32_dpp v16, v16, v16 row_mirror row_mask:0xf bank_mask:0xf
	v_add_f32_dpp v18, v18, v18 row_mirror row_mask:0xf bank_mask:0xf
	v_add_f32_dpp v20, v20, v20 row_mirror row_mask:0xf bank_mask:0xf
	v_add_f32_dpp v22, v22, v22 row_mirror row_mask:0xf bank_mask:0xf
	v_add_f32_dpp v24, v24, v24 row_mirror row_mask:0xf bank_mask:0xf
	v_add_f32_dpp v26, v26, v26 row_mirror row_mask:0xf bank_mask:0xf
	v_add_f32_dpp v28, v28, v28 row_mirror row_mask:0xf bank_mask:0xf
	v_add_f32_dpp v30, v30, v30 row_mirror row_mask:0xf bank_mask:0xf
	v_add_f32_dpp v16, v16, v16 row_bcast:15 row_mask:0xa bank_mask:0xf
	v_add_f32_dpp v18, v18, v18 row_bcast:15 row_mask:0xa bank_mask:0xf
	v_add_f32_dpp v20, v20, v20 row_bcast:15 row_mask:0xa bank_mask:0xf
	v_add_f32_dpp v22, v22, v22 row_bcast:15 row_mask:0xa bank_mask:0xf
	v_add_f32_dpp v24, v24, v24 row_bcast:15 row_mask:0xa bank_mask:0xf
	v_add_f32_dpp v26, v26, v26 row_bcast:15 row_mask:0xa bank_mask:0xf
	v_add_f32_dpp v28, v28, v28 row_bcast:15 row_mask:0xa bank_mask:0xf
	v_add_f32_dpp v30, v30, v30 row_bcast:15 row_mask:0xa bank_mask:0xf
	v_add_f32_dpp v16, v16, v16 row_bcast:31 row_mask:0xc bank_mask:0xf
	v_add_f32_dpp v18, v18, v18 row_bcast:31 row_mask:0xc bank_mask:0xf
	v_add_f32_dpp v20, v20, v20 row_bcast:31 row_mask:0xc bank_mask:0xf
	v_add_f32_dpp v22, v22, v22 row_bcast:31 row_mask:0xc bank_mask:0xf
	v_add_f32_dpp v24, v24, v24 row_bcast:31 row_mask:0xc bank_mask:0xf
	v_add_f32_dpp v26, v26, v26 row_bcast:31 row_mask:0xc bank_mask:0xf
	v_add_f32_dpp v28, v28, v28 row_bcast:31 row_mask:0xc bank_mask:0xf
	v_add_f32_dpp v30, v30, v30 row_bcast:31 row_mask:0xc bank_mask:0xf
	s_nop 0
	v_readlane_b32 s14, v16, 63
	v_readlane_b32 s15, v18, 63
	v_readlane_b32 s16, v20, 63
	v_readlane_b32 s17, v22, 63
	v_readlane_b32 s18, v24, 63
	v_readlane_b32 s19, v26, 63
	v_readlane_b32 s46, v28, 63
	v_readlane_b32 s47, v30, 63
	s_nop 1
	v_writelane_b32 v4, s14, 56
	v_writelane_b32 v4, s15, 57
	v_writelane_b32 v4, s16, 58
	v_writelane_b32 v4, s17, 59
	v_writelane_b32 v4, s18, 60
	v_writelane_b32 v4, s19, 61
	v_writelane_b32 v4, s46, 62
	v_writelane_b32 v4, s47, 63
	s_mov_b32 s62, s8
	s_movk_i32 s6, 64
; __device__ __forceinline__ void p0_prologue(const Args& a, LAS unsigned char* lds, int vcu, int G, int tid, int lane, int wave) {
;     ...
;         float fz = f[0];
; #pragma unroll
;         for (int h = 1; h < 8; ++h) fz = (lane == h) ? f[h] : fz;
;         if (lane < 8) { const float z = fz + b_f[lane]; const float ls = fminf(z, 0.f) - log1pf(expf(-fabsf(z)));
;             const int b = m >> 12, s = m & 4095; logf_[((size_t)(b * NH + lane) << 12) + s] = ls; }
.Lp0r_flush:
	v_cmp_gt_u32_e32 vcc, s6, v1
	s_and_saveexec_b64 s[38:39], vcc
	v_lshrrev_b32_e32 v38, 3, v1
	v_mul_lo_u32 v39, v38, s34
	v_add_u32_e32 v39, s64, v39
	v_lshrrev_b32_e32 v40, 12, v39
	v_and_b32_e32 v41, 0xfff, v39
	v_and_b32_e32 v38, 7, v1
	v_lshl_or_b32 v40, v40, 3, v38
	v_lshl_or_b32 v40, v40, 12, v41
	v_lshlrev_b32_e32 v40, 2, v40
	v_add_f32_e32 v18, v4, v5
	v_mul_f32_e64 v19, |v18|, s35
	v_fma_f32 v20, |v18|, s35, -v19
	v_rndne_f32_e32 v21, v19
	v_fma_f32 v20, |v18|, s54, v20
	v_sub_f32_e32 v19, v19, v21
	v_add_f32_e32 v19, v19, v20
	v_cvt_i32_f32_e32 v21, v21
	v_exp_f32_e32 v19, v19
	v_cmp_ngt_f32_e64 vcc, |v18|, s55
	v_min_f32_e32 v34, 0, v18
	v_ldexp_f32 v19, v19, v21
	v_cndmask_b32_e32 v19, 0, v19, vcc
	v_cmp_nlt_f32_e64 vcc, |v18|, s56
	s_nop 1
	v_cndmask_b32_e32 v35, v37, v19, vcc
	v_add_f32_e32 v20, 1.0, v35
	v_add_f32_e32 v21, -1.0, v20
	v_frexp_mant_f32_e32 v22, v20
	v_cvt_f64_f32_e32 v[18:19], v20
	v_sub_f32_e32 v23, v21, v20
	v_frexp_exp_i32_f64_e32 v18, v[18:19]
	v_cmp_gt_f32_e32 vcc, s58, v22
	v_sub_f32_e32 v21, v35, v21
	v_add_f32_e32 v19, 1.0, v23
	v_subbrev_co_u32_e32 v18, vcc, 0, v18, vcc
	v_add_f32_e32 v19, v21, v19
	v_sub_u32_e32 v21, 0, v18
	v_ldexp_f32 v20, v20, v21
	v_add_f32_e32 v22, -1.0, v20
	v_add_f32_e32 v23, 1.0, v20
	v_ldexp_f32 v19, v19, v21
	v_add_f32_e32 v21, 1.0, v22
	v_add_f32_e32 v24, -1.0, v23
	v_sub_f32_e32 v21, v20, v21
	v_sub_f32_e32 v20, v20, v24
	v_add_f32_e32 v24, v19, v21
	v_add_f32_e32 v19, v19, v20
	v_add_f32_e32 v26, v23, v19
	v_rcp_f32_e32 v27, v26
	v_add_f32_e32 v21, v22, v24
	v_sub_f32_e32 v22, v22, v21
	v_sub_f32_e32 v20, v23, v26
	v_mul_f32_e32 v29, v21, v27
	v_add_f32_e32 v28, v24, v22
	v_mul_f32_e32 v22, v26, v29
	v_add_f32_e32 v19, v19, v20
	v_fma_f32 v24, v29, v26, -v22
	v_fmac_f32_e32 v24, v29, v19
	v_add_f32_e32 v20, v22, v24
	v_sub_f32_e32 v23, v21, v20
	v_mov_b32_e32 v25, v20
	v_pk_add_f32 v[20:21], v[20:21], v[22:23] neg_lo:[0,1] neg_hi:[0,1]
	v_cvt_f32_i32_e32 v18, v18
	v_pk_add_f32 v[20:21], v[20:21], v[24:25] neg_lo:[0,1] neg_hi:[0,1]
	v_cmp_neq_f32_e32 vcc, s57, v35
	v_add_f32_e32 v21, v28, v21
	v_add_f32_e32 v20, v20, v21
	v_add_f32_e32 v21, v23, v20
	v_mul_f32_e32 v25, v27, v21
	v_mul_f32_e32 v22, v26, v25
	v_sub_f32_e32 v23, v23, v21
	v_add_f32_e32 v30, v29, v25
	v_fma_f32 v24, v25, v26, -v22
	v_add_f32_e32 v28, v20, v23
	v_sub_f32_e32 v20, v30, v29
	v_fmac_f32_e32 v24, v25, v19
	v_sub_f32_e32 v19, v25, v20
	v_add_f32_e32 v20, v22, v24
	v_sub_f32_e32 v23, v21, v20
	v_mov_b32_e32 v25, v20
	v_pk_add_f32 v[20:21], v[20:21], v[22:23] neg_lo:[0,1] neg_hi:[0,1]
	s_nop 0
	v_pk_add_f32 v[20:21], v[20:21], v[24:25] neg_lo:[0,1] neg_hi:[0,1]
	s_nop 0
	v_add_f32_e32 v21, v28, v21
	v_add_f32_e32 v20, v20, v21
	v_add_f32_e32 v20, v23, v20
	v_mul_f32_e32 v20, v27, v20
	v_add_f32_e32 v19, v19, v20
	v_add_f32_e32 v20, v30, v19
	v_mul_f32_e32 v22, v20, v20
	v_sub_f32_e32 v23, v20, v30
	v_fmamk_f32 v24, v22, 0x3e9b6dac, v36
	v_sub_f32_e32 v23, v19, v23
	v_mul_f32_e32 v19, v20, v22
	v_fmaak_f32 v33, v22, v24, 0x3f2aaada
	v_ldexp_f32 v25, v23, 1
	v_pk_mul_f32 v[22:23], v[18:19], v[32:33]
	v_ldexp_f32 v21, v20, 1
	v_fma_f32 v20, v18, s59, -v22
	v_fmac_f32_e32 v20, 0xb102e308, v18
	v_pk_add_f32 v[18:19], v[22:23], v[20:21]
	v_mov_b32_e32 v24, v22
	v_sub_f32_e32 v28, v19, v21
	v_pk_add_f32 v[26:27], v[18:19], v[22:23] neg_lo:[0,1] neg_hi:[0,1]
	v_sub_f32_e32 v22, v23, v28
	v_add_f32_e32 v25, v25, v22
	v_pk_add_f32 v[22:23], v[18:19], v[24:25]
	v_mov_b32_e32 v21, v18
	v_mov_b32_e32 v27, v23
	v_pk_add_f32 v[30:31], v[20:21], v[26:27] neg_lo:[0,1] neg_hi:[0,1]
	v_pk_add_f32 v[20:21], v[20:21], v[26:27]
	v_mov_b32_e32 v29, v18
	v_pk_add_f32 v[26:27], v[20:21], v[18:19] op_sel:[1,0] op_sel_hi:[0,1] neg_lo:[0,1] neg_hi:[0,1]
	v_mov_b32_e32 v28, v25
	v_mov_b32_e32 v24, v23
	v_mov_b32_e32 v25, v21
	v_pk_mov_b32 v[18:19], v[18:19], v[26:27] op_sel:[1,0]
	v_pk_add_f32 v[22:23], v[22:23], v[26:27] op_sel_hi:[1,0] neg_lo:[0,1] neg_hi:[0,1]
	v_pk_add_f32 v[18:19], v[24:25], v[18:19] neg_lo:[0,1] neg_hi:[0,1]
	v_mov_b32_e32 v22, v30
	v_pk_add_f32 v[18:19], v[28:29], v[18:19] neg_lo:[0,1] neg_hi:[0,1]
	v_mov_b32_e32 v31, v21
	v_pk_add_f32 v[22:23], v[22:23], v[18:19]
	s_nop 0
	v_pk_add_f32 v[24:25], v[22:23], v[22:23] op_sel:[0,1] op_sel_hi:[1,0]
	s_nop 0
	v_pk_add_f32 v[20:21], v[20:21], v[24:25] op_sel:[1,0] op_sel_hi:[0,1]
	v_mov_b32_e32 v23, v20
	v_mov_b32_e32 v19, v24
	v_pk_add_f32 v[24:25], v[22:23], v[30:31] neg_lo:[0,1] neg_hi:[0,1]
	s_nop 0
	v_sub_f32_e32 v21, v22, v24
	v_pk_add_f32 v[18:19], v[18:19], v[24:25] neg_lo:[0,1] neg_hi:[0,1]
	v_sub_f32_e32 v21, v30, v21
	v_add_f32_e32 v18, v18, v21
	v_add_f32_e32 v18, v18, v19
	v_add_f32_e32 v18, v20, v18
	v_cndmask_b32_e32 v18, v37, v18, vcc
	v_cmp_lt_f32_e64 vcc, |v35|, s63
	s_nop 1
	v_cndmask_b32_e32 v18, v18, v35, vcc
	v_sub_f32_e32 v18, v34, v18
	global_store_dword v40, v18, s[20:21]
	s_or_b64 exec, exec, s[38:39]
	s_mov_b32 s64, s62
	s_cmp_lt_i32 s62, 32768
	s_cbranch_scc1 .Lp0r_row0
